# v037 + TOPK rewritten by hand: register-resident bitonic sort (4 keys per thread, ds_bpermute within a wave, LDS only for the 6 cross-wave steps), same keys and order as before
# speedup vs baseline: 1.0130x; 1.0130x over previous
.LBB0_1335:
	s_waitcnt lgkmcnt(0)
	s_barrier
	v_mbcnt_lo_u32_b32 v0, -1, 0
	v_mbcnt_hi_u32_b32 v0, -1, v0
	v_readlane_b32 s22, v255, 11
	v_readlane_b32 s34, v255, 6
	v_readlane_b32 s35, v255, 7
	s_mov_b32 s0, 0xaaaaaaaa
	s_mov_b32 s1, 0xaaaaaaaa
	s_mov_b32 s2, 0xcccccccc
	s_mov_b32 s3, 0xcccccccc
	s_mov_b32 s4, 0xf0f0f0f0
	s_mov_b32 s5, 0xf0f0f0f0
	s_mov_b32 s6, 0xff00ff00
	s_mov_b32 s7, 0xff00ff00
	s_mov_b32 s8, 0xffff0000
	s_mov_b32 s9, 0xffff0000
	s_mov_b32 s10, 0
	s_mov_b32 s11, -1
	v_xor_b32_e32 v196, 1, v0
	v_lshlrev_b32_e32 v196, 2, v196
	v_xor_b32_e32 v197, 2, v0
	v_lshlrev_b32_e32 v197, 2, v197
	v_xor_b32_e32 v198, 4, v0
	v_lshlrev_b32_e32 v198, 2, v198
	v_xor_b32_e32 v199, 8, v0
	v_lshlrev_b32_e32 v199, 2, v199
	v_xor_b32_e32 v200, 16, v0
	v_lshlrev_b32_e32 v200, 2, v200
	v_xor_b32_e32 v201, 32, v0
	v_lshlrev_b32_e32 v201, 2, v201
	v_lshl_add_u32 v18, s22, 6, v0
	v_lshlrev_b32_e32 v202, 5, v18
	v_xor_b32_e32 v203, 0x800, v202
	v_xor_b32_e32 v204, 0x1000, v202
	v_xor_b32_e32 v205, 0x2000, v202
	s_mov_b32 s24, s84
	s_cmp_eq_u32 s55, 3
	s_movk_i32 s25, 0x200
	s_cselect_b32 s25, 0x100, s25
.Ltks_item:
	s_cmp_ge_i32 s24, s25
	s_cbranch_scc1 .Ltks_done
	s_cmp_lt_i32 s24, 0x100
	s_movk_i32 s26, 0x800
	s_cselect_b32 s26, s26, 0x100
	s_cselect_b32 s27, 64, 8
	s_cselect_b32 s31, 0, 0x100
	s_sub_i32 s31, s24, s31
	s_lshr_b32 s33, s31, 4
	s_and_b32 s30, s31, 15
	s_lshl_b32 s28, s33, 11
	s_lshl_b32 s29, s33, 8
	s_lshl_b32 s31, s33, 5
	s_addk_i32 s31, 0x1000
	s_add_i32 s33, s29, 0x8000
	s_cmp_lt_i32 s24, 0x100
	s_cselect_b32 s28, s28, s33
	s_cselect_b32 s29, s29, s31
	s_lshl_b32 s33, s28, 4
	s_add_i32 s33, s33, s30
	s_lshl_b32 s33, s33, 2
	s_add_u32 s98, s34, 0x400000
	s_addc_u32 s99, s35, 0
	s_add_i32 s31, s26, -1
	v_mov_b32_e32 v206, v18
	v_add_u32_e32 v207, 512, v18
	v_add_u32_e32 v208, 1024, v18
	v_add_u32_e32 v209, 1536, v18
	v_min_u32_e32 v210, s31, v206
	v_min_u32_e32 v211, s31, v207
	v_min_u32_e32 v212, s31, v208
	v_min_u32_e32 v213, s31, v209
	v_lshl_add_u32 v210, v210, 6, s33
	v_lshl_add_u32 v211, v211, 6, s33
	v_lshl_add_u32 v212, v212, 6, s33
	v_lshl_add_u32 v213, v213, 6, s33
	global_load_dword v3, v210, s[98:99]
	global_load_dword v5, v211, s[98:99]
	global_load_dword v7, v212, s[98:99]
	global_load_dword v9, v213, s[98:99]
	v_cmp_gt_u32_e64 s[14:15], s26, v206
	v_not_b32_e32 v2, v206
	v_cmp_gt_u32_e64 s[16:17], s26, v207
	v_not_b32_e32 v4, v207
	v_cmp_gt_u32_e64 s[18:19], s26, v208
	v_not_b32_e32 v6, v208
	v_cmp_gt_u32_e64 s[20:21], s26, v209
	v_not_b32_e32 v8, v209
	v_cndmask_b32_e64 v2, 0, v2, s[14:15]
	v_cndmask_b32_e64 v4, 0, v4, s[16:17]
	v_cndmask_b32_e64 v6, 0, v6, s[18:19]
	v_cndmask_b32_e64 v8, 0, v8, s[20:21]
	s_waitcnt vmcnt(0)
	v_cndmask_b32_e64 v3, 0, v3, s[14:15]
	v_cndmask_b32_e64 v5, 0, v5, s[16:17]
	v_cndmask_b32_e64 v7, 0, v7, s[18:19]
	v_cndmask_b32_e64 v9, 0, v9, s[20:21]
	v_cmp_lt_u64_e64 s[14:15], v[2:3], v[4:5]
	v_cmp_gt_u64_e64 s[16:17], v[6:7], v[8:9]
	s_nop 1
	v_cndmask_b32_e64 v188, v2, v4, s[14:15]
	v_cndmask_b32_e64 v189, v3, v5, s[14:15]
	v_cndmask_b32_e64 v190, v4, v2, s[14:15]
	v_cndmask_b32_e64 v191, v5, v3, s[14:15]
	v_cndmask_b32_e64 v192, v6, v8, s[16:17]
	v_cndmask_b32_e64 v193, v7, v9, s[16:17]
	v_cndmask_b32_e64 v194, v8, v6, s[16:17]
	v_cndmask_b32_e64 v195, v9, v7, s[16:17]
	s_not_b64 s[12:13], s[0:1]
	v_cmp_gt_u64_e64 s[14:15], v[188:189], v[192:193]
	v_cmp_gt_u64_e64 s[16:17], v[190:191], v[194:195]
	s_xor_b64 s[14:15], s[14:15], s[12:13]
	s_xor_b64 s[16:17], s[16:17], s[12:13]
	v_cndmask_b32_e64 v2, v188, v192, s[14:15]
	v_cndmask_b32_e64 v3, v189, v193, s[14:15]
	v_cndmask_b32_e64 v6, v192, v188, s[14:15]
	v_cndmask_b32_e64 v7, v193, v189, s[14:15]
	v_cndmask_b32_e64 v4, v190, v194, s[16:17]
	v_cndmask_b32_e64 v5, v191, v195, s[16:17]
	v_cndmask_b32_e64 v8, v194, v190, s[16:17]
	v_cndmask_b32_e64 v9, v195, v191, s[16:17]
	s_not_b64 s[12:13], s[0:1]
	v_cmp_gt_u64_e64 s[14:15], v[2:3], v[4:5]
	v_cmp_gt_u64_e64 s[16:17], v[6:7], v[8:9]
	s_xor_b64 s[14:15], s[14:15], s[12:13]
	s_xor_b64 s[16:17], s[16:17], s[12:13]
	v_cndmask_b32_e64 v188, v2, v4, s[14:15]
	v_cndmask_b32_e64 v189, v3, v5, s[14:15]
	v_cndmask_b32_e64 v190, v4, v2, s[14:15]
	v_cndmask_b32_e64 v191, v5, v3, s[14:15]
	v_cndmask_b32_e64 v192, v6, v8, s[16:17]
	v_cndmask_b32_e64 v193, v7, v9, s[16:17]
	v_cndmask_b32_e64 v194, v8, v6, s[16:17]
	v_cndmask_b32_e64 v195, v9, v7, s[16:17]
	s_xnor_b64 s[12:13], s[2:3], s[0:1]
	ds_bpermute_b32 v10, v196, v188
	ds_bpermute_b32 v11, v196, v189
	ds_bpermute_b32 v12, v196, v190
	ds_bpermute_b32 v13, v196, v191
	ds_bpermute_b32 v14, v196, v192
	ds_bpermute_b32 v15, v196, v193
	ds_bpermute_b32 v16, v196, v194
	ds_bpermute_b32 v17, v196, v195
	s_waitcnt lgkmcnt(6)
	v_cmp_gt_u64_e64 s[14:15], v[188:189], v[10:11]
	s_waitcnt lgkmcnt(4)
	v_cmp_gt_u64_e64 s[16:17], v[190:191], v[12:13]
	s_waitcnt lgkmcnt(2)
	v_cmp_gt_u64_e64 s[18:19], v[192:193], v[14:15]
	s_waitcnt lgkmcnt(0)
	v_cmp_gt_u64_e64 s[20:21], v[194:195], v[16:17]
	s_xor_b64 s[14:15], s[14:15], s[12:13]
	s_xor_b64 s[16:17], s[16:17], s[12:13]
	s_xor_b64 s[18:19], s[18:19], s[12:13]
	s_xor_b64 s[20:21], s[20:21], s[12:13]
	v_cndmask_b32_e64 v188, v188, v10, s[14:15]
	v_cndmask_b32_e64 v189, v189, v11, s[14:15]
	v_cndmask_b32_e64 v190, v190, v12, s[16:17]
	v_cndmask_b32_e64 v191, v191, v13, s[16:17]
	v_cndmask_b32_e64 v192, v192, v14, s[18:19]
	v_cndmask_b32_e64 v193, v193, v15, s[18:19]
	v_cndmask_b32_e64 v194, v194, v16, s[20:21]
	v_cndmask_b32_e64 v195, v195, v17, s[20:21]
	s_not_b64 s[12:13], s[2:3]
	v_cmp_gt_u64_e64 s[14:15], v[188:189], v[192:193]
	v_cmp_gt_u64_e64 s[16:17], v[190:191], v[194:195]
	s_xor_b64 s[14:15], s[14:15], s[12:13]
	s_xor_b64 s[16:17], s[16:17], s[12:13]
	v_cndmask_b32_e64 v2, v188, v192, s[14:15]
	v_cndmask_b32_e64 v3, v189, v193, s[14:15]
	v_cndmask_b32_e64 v6, v192, v188, s[14:15]
	v_cndmask_b32_e64 v7, v193, v189, s[14:15]
	v_cndmask_b32_e64 v4, v190, v194, s[16:17]
	v_cndmask_b32_e64 v5, v191, v195, s[16:17]
	v_cndmask_b32_e64 v8, v194, v190, s[16:17]
	v_cndmask_b32_e64 v9, v195, v191, s[16:17]
	s_not_b64 s[12:13], s[2:3]
	v_cmp_gt_u64_e64 s[14:15], v[2:3], v[4:5]
	v_cmp_gt_u64_e64 s[16:17], v[6:7], v[8:9]
	s_xor_b64 s[14:15], s[14:15], s[12:13]
	s_xor_b64 s[16:17], s[16:17], s[12:13]
	v_cndmask_b32_e64 v188, v2, v4, s[14:15]
	v_cndmask_b32_e64 v189, v3, v5, s[14:15]
	v_cndmask_b32_e64 v190, v4, v2, s[14:15]
	v_cndmask_b32_e64 v191, v5, v3, s[14:15]
	v_cndmask_b32_e64 v192, v6, v8, s[16:17]
	v_cndmask_b32_e64 v193, v7, v9, s[16:17]
	v_cndmask_b32_e64 v194, v8, v6, s[16:17]
	v_cndmask_b32_e64 v195, v9, v7, s[16:17]
	s_xnor_b64 s[12:13], s[4:5], s[2:3]
	ds_bpermute_b32 v10, v197, v188
	ds_bpermute_b32 v11, v197, v189
	ds_bpermute_b32 v12, v197, v190
	ds_bpermute_b32 v13, v197, v191
	ds_bpermute_b32 v14, v197, v192
	ds_bpermute_b32 v15, v197, v193
	ds_bpermute_b32 v16, v197, v194
	ds_bpermute_b32 v17, v197, v195
	s_waitcnt lgkmcnt(6)
	v_cmp_gt_u64_e64 s[14:15], v[188:189], v[10:11]
	s_waitcnt lgkmcnt(4)
	v_cmp_gt_u64_e64 s[16:17], v[190:191], v[12:13]
	s_waitcnt lgkmcnt(2)
	v_cmp_gt_u64_e64 s[18:19], v[192:193], v[14:15]
	s_waitcnt lgkmcnt(0)
	v_cmp_gt_u64_e64 s[20:21], v[194:195], v[16:17]
	s_xor_b64 s[14:15], s[14:15], s[12:13]
	s_xor_b64 s[16:17], s[16:17], s[12:13]
	s_xor_b64 s[18:19], s[18:19], s[12:13]
	s_xor_b64 s[20:21], s[20:21], s[12:13]
	v_cndmask_b32_e64 v188, v188, v10, s[14:15]
	v_cndmask_b32_e64 v189, v189, v11, s[14:15]
	v_cndmask_b32_e64 v190, v190, v12, s[16:17]
	v_cndmask_b32_e64 v191, v191, v13, s[16:17]
	v_cndmask_b32_e64 v192, v192, v14, s[18:19]
	v_cndmask_b32_e64 v193, v193, v15, s[18:19]
	v_cndmask_b32_e64 v194, v194, v16, s[20:21]
	v_cndmask_b32_e64 v195, v195, v17, s[20:21]
	s_xnor_b64 s[12:13], s[4:5], s[0:1]
	ds_bpermute_b32 v10, v196, v188
	ds_bpermute_b32 v11, v196, v189
	ds_bpermute_b32 v12, v196, v190
	ds_bpermute_b32 v13, v196, v191
	ds_bpermute_b32 v14, v196, v192
	ds_bpermute_b32 v15, v196, v193
	ds_bpermute_b32 v16, v196, v194
	ds_bpermute_b32 v17, v196, v195
	s_waitcnt lgkmcnt(6)
	v_cmp_gt_u64_e64 s[14:15], v[188:189], v[10:11]
	s_waitcnt lgkmcnt(4)
	v_cmp_gt_u64_e64 s[16:17], v[190:191], v[12:13]
	s_waitcnt lgkmcnt(2)
	v_cmp_gt_u64_e64 s[18:19], v[192:193], v[14:15]
	s_waitcnt lgkmcnt(0)
	v_cmp_gt_u64_e64 s[20:21], v[194:195], v[16:17]
	s_xor_b64 s[14:15], s[14:15], s[12:13]
	s_xor_b64 s[16:17], s[16:17], s[12:13]
	s_xor_b64 s[18:19], s[18:19], s[12:13]
	s_xor_b64 s[20:21], s[20:21], s[12:13]
	v_cndmask_b32_e64 v188, v188, v10, s[14:15]
	v_cndmask_b32_e64 v189, v189, v11, s[14:15]
	v_cndmask_b32_e64 v190, v190, v12, s[16:17]
	v_cndmask_b32_e64 v191, v191, v13, s[16:17]
	v_cndmask_b32_e64 v192, v192, v14, s[18:19]
	v_cndmask_b32_e64 v193, v193, v15, s[18:19]
	v_cndmask_b32_e64 v194, v194, v16, s[20:21]
	v_cndmask_b32_e64 v195, v195, v17, s[20:21]
	s_not_b64 s[12:13], s[4:5]
	v_cmp_gt_u64_e64 s[14:15], v[188:189], v[192:193]
	v_cmp_gt_u64_e64 s[16:17], v[190:191], v[194:195]
	s_xor_b64 s[14:15], s[14:15], s[12:13]
	s_xor_b64 s[16:17], s[16:17], s[12:13]
	v_cndmask_b32_e64 v2, v188, v192, s[14:15]
	v_cndmask_b32_e64 v3, v189, v193, s[14:15]
	v_cndmask_b32_e64 v6, v192, v188, s[14:15]
	v_cndmask_b32_e64 v7, v193, v189, s[14:15]
	v_cndmask_b32_e64 v4, v190, v194, s[16:17]
	v_cndmask_b32_e64 v5, v191, v195, s[16:17]
	v_cndmask_b32_e64 v8, v194, v190, s[16:17]
	v_cndmask_b32_e64 v9, v195, v191, s[16:17]
	s_not_b64 s[12:13], s[4:5]
	v_cmp_gt_u64_e64 s[14:15], v[2:3], v[4:5]
	v_cmp_gt_u64_e64 s[16:17], v[6:7], v[8:9]
	s_xor_b64 s[14:15], s[14:15], s[12:13]
	s_xor_b64 s[16:17], s[16:17], s[12:13]
	v_cndmask_b32_e64 v188, v2, v4, s[14:15]
	v_cndmask_b32_e64 v189, v3, v5, s[14:15]
	v_cndmask_b32_e64 v190, v4, v2, s[14:15]
	v_cndmask_b32_e64 v191, v5, v3, s[14:15]
	v_cndmask_b32_e64 v192, v6, v8, s[16:17]
	v_cndmask_b32_e64 v193, v7, v9, s[16:17]
	v_cndmask_b32_e64 v194, v8, v6, s[16:17]
	v_cndmask_b32_e64 v195, v9, v7, s[16:17]
	s_xnor_b64 s[12:13], s[6:7], s[4:5]
	ds_bpermute_b32 v10, v198, v188
	ds_bpermute_b32 v11, v198, v189
	ds_bpermute_b32 v12, v198, v190
	ds_bpermute_b32 v13, v198, v191
	ds_bpermute_b32 v14, v198, v192
	ds_bpermute_b32 v15, v198, v193
	ds_bpermute_b32 v16, v198, v194
	ds_bpermute_b32 v17, v198, v195
	s_waitcnt lgkmcnt(6)
	v_cmp_gt_u64_e64 s[14:15], v[188:189], v[10:11]
	s_waitcnt lgkmcnt(4)
	v_cmp_gt_u64_e64 s[16:17], v[190:191], v[12:13]
	s_waitcnt lgkmcnt(2)
	v_cmp_gt_u64_e64 s[18:19], v[192:193], v[14:15]
	s_waitcnt lgkmcnt(0)
	v_cmp_gt_u64_e64 s[20:21], v[194:195], v[16:17]
	s_xor_b64 s[14:15], s[14:15], s[12:13]
	s_xor_b64 s[16:17], s[16:17], s[12:13]
	s_xor_b64 s[18:19], s[18:19], s[12:13]
	s_xor_b64 s[20:21], s[20:21], s[12:13]
	v_cndmask_b32_e64 v188, v188, v10, s[14:15]
	v_cndmask_b32_e64 v189, v189, v11, s[14:15]
	v_cndmask_b32_e64 v190, v190, v12, s[16:17]
	v_cndmask_b32_e64 v191, v191, v13, s[16:17]
	v_cndmask_b32_e64 v192, v192, v14, s[18:19]
	v_cndmask_b32_e64 v193, v193, v15, s[18:19]
	v_cndmask_b32_e64 v194, v194, v16, s[20:21]
	v_cndmask_b32_e64 v195, v195, v17, s[20:21]
	s_xnor_b64 s[12:13], s[6:7], s[2:3]
	ds_bpermute_b32 v10, v197, v188
	ds_bpermute_b32 v11, v197, v189
	ds_bpermute_b32 v12, v197, v190
	ds_bpermute_b32 v13, v197, v191
	ds_bpermute_b32 v14, v197, v192
	ds_bpermute_b32 v15, v197, v193
	ds_bpermute_b32 v16, v197, v194
	ds_bpermute_b32 v17, v197, v195
	s_waitcnt lgkmcnt(6)
	v_cmp_gt_u64_e64 s[14:15], v[188:189], v[10:11]
	s_waitcnt lgkmcnt(4)
	v_cmp_gt_u64_e64 s[16:17], v[190:191], v[12:13]
	s_waitcnt lgkmcnt(2)
	v_cmp_gt_u64_e64 s[18:19], v[192:193], v[14:15]
	s_waitcnt lgkmcnt(0)
	v_cmp_gt_u64_e64 s[20:21], v[194:195], v[16:17]
	s_xor_b64 s[14:15], s[14:15], s[12:13]
	s_xor_b64 s[16:17], s[16:17], s[12:13]
	s_xor_b64 s[18:19], s[18:19], s[12:13]
	s_xor_b64 s[20:21], s[20:21], s[12:13]
	v_cndmask_b32_e64 v188, v188, v10, s[14:15]
	v_cndmask_b32_e64 v189, v189, v11, s[14:15]
	v_cndmask_b32_e64 v190, v190, v12, s[16:17]
	v_cndmask_b32_e64 v191, v191, v13, s[16:17]
	v_cndmask_b32_e64 v192, v192, v14, s[18:19]
	v_cndmask_b32_e64 v193, v193, v15, s[18:19]
	v_cndmask_b32_e64 v194, v194, v16, s[20:21]
	v_cndmask_b32_e64 v195, v195, v17, s[20:21]
	s_xnor_b64 s[12:13], s[6:7], s[0:1]
	ds_bpermute_b32 v10, v196, v188
	ds_bpermute_b32 v11, v196, v189
	ds_bpermute_b32 v12, v196, v190
	ds_bpermute_b32 v13, v196, v191
	ds_bpermute_b32 v14, v196, v192
	ds_bpermute_b32 v15, v196, v193
	ds_bpermute_b32 v16, v196, v194
	ds_bpermute_b32 v17, v196, v195
	s_waitcnt lgkmcnt(6)
	v_cmp_gt_u64_e64 s[14:15], v[188:189], v[10:11]
	s_waitcnt lgkmcnt(4)
	v_cmp_gt_u64_e64 s[16:17], v[190:191], v[12:13]
	s_waitcnt lgkmcnt(2)
	v_cmp_gt_u64_e64 s[18:19], v[192:193], v[14:15]
	s_waitcnt lgkmcnt(0)
	v_cmp_gt_u64_e64 s[20:21], v[194:195], v[16:17]
	s_xor_b64 s[14:15], s[14:15], s[12:13]
	s_xor_b64 s[16:17], s[16:17], s[12:13]
	s_xor_b64 s[18:19], s[18:19], s[12:13]
	s_xor_b64 s[20:21], s[20:21], s[12:13]
	v_cndmask_b32_e64 v188, v188, v10, s[14:15]
	v_cndmask_b32_e64 v189, v189, v11, s[14:15]
	v_cndmask_b32_e64 v190, v190, v12, s[16:17]
	v_cndmask_b32_e64 v191, v191, v13, s[16:17]
	v_cndmask_b32_e64 v192, v192, v14, s[18:19]
	v_cndmask_b32_e64 v193, v193, v15, s[18:19]
	v_cndmask_b32_e64 v194, v194, v16, s[20:21]
	v_cndmask_b32_e64 v195, v195, v17, s[20:21]
	s_not_b64 s[12:13], s[6:7]
	v_cmp_gt_u64_e64 s[14:15], v[188:189], v[192:193]
	v_cmp_gt_u64_e64 s[16:17], v[190:191], v[194:195]
	s_xor_b64 s[14:15], s[14:15], s[12:13]
	s_xor_b64 s[16:17], s[16:17], s[12:13]
	v_cndmask_b32_e64 v2, v188, v192, s[14:15]
	v_cndmask_b32_e64 v3, v189, v193, s[14:15]
	v_cndmask_b32_e64 v6, v192, v188, s[14:15]
	v_cndmask_b32_e64 v7, v193, v189, s[14:15]
	v_cndmask_b32_e64 v4, v190, v194, s[16:17]
	v_cndmask_b32_e64 v5, v191, v195, s[16:17]
	v_cndmask_b32_e64 v8, v194, v190, s[16:17]
	v_cndmask_b32_e64 v9, v195, v191, s[16:17]
	s_not_b64 s[12:13], s[6:7]
	v_cmp_gt_u64_e64 s[14:15], v[2:3], v[4:5]
	v_cmp_gt_u64_e64 s[16:17], v[6:7], v[8:9]
	s_xor_b64 s[14:15], s[14:15], s[12:13]
	s_xor_b64 s[16:17], s[16:17], s[12:13]
	v_cndmask_b32_e64 v188, v2, v4, s[14:15]
	v_cndmask_b32_e64 v189, v3, v5, s[14:15]
	v_cndmask_b32_e64 v190, v4, v2, s[14:15]
	v_cndmask_b32_e64 v191, v5, v3, s[14:15]
	v_cndmask_b32_e64 v192, v6, v8, s[16:17]
	v_cndmask_b32_e64 v193, v7, v9, s[16:17]
	v_cndmask_b32_e64 v194, v8, v6, s[16:17]
	v_cndmask_b32_e64 v195, v9, v7, s[16:17]
	s_xnor_b64 s[12:13], s[8:9], s[6:7]
	ds_bpermute_b32 v10, v199, v188
	ds_bpermute_b32 v11, v199, v189
	ds_bpermute_b32 v12, v199, v190
	ds_bpermute_b32 v13, v199, v191
	ds_bpermute_b32 v14, v199, v192
	ds_bpermute_b32 v15, v199, v193
	ds_bpermute_b32 v16, v199, v194
	ds_bpermute_b32 v17, v199, v195
	s_waitcnt lgkmcnt(6)
	v_cmp_gt_u64_e64 s[14:15], v[188:189], v[10:11]
	s_waitcnt lgkmcnt(4)
	v_cmp_gt_u64_e64 s[16:17], v[190:191], v[12:13]
	s_waitcnt lgkmcnt(2)
	v_cmp_gt_u64_e64 s[18:19], v[192:193], v[14:15]
	s_waitcnt lgkmcnt(0)
	v_cmp_gt_u64_e64 s[20:21], v[194:195], v[16:17]
	s_xor_b64 s[14:15], s[14:15], s[12:13]
	s_xor_b64 s[16:17], s[16:17], s[12:13]
	s_xor_b64 s[18:19], s[18:19], s[12:13]
	s_xor_b64 s[20:21], s[20:21], s[12:13]
	v_cndmask_b32_e64 v188, v188, v10, s[14:15]
	v_cndmask_b32_e64 v189, v189, v11, s[14:15]
	v_cndmask_b32_e64 v190, v190, v12, s[16:17]
	v_cndmask_b32_e64 v191, v191, v13, s[16:17]
	v_cndmask_b32_e64 v192, v192, v14, s[18:19]
	v_cndmask_b32_e64 v193, v193, v15, s[18:19]
	v_cndmask_b32_e64 v194, v194, v16, s[20:21]
	v_cndmask_b32_e64 v195, v195, v17, s[20:21]
	s_xnor_b64 s[12:13], s[8:9], s[4:5]
	ds_bpermute_b32 v10, v198, v188
	ds_bpermute_b32 v11, v198, v189
	ds_bpermute_b32 v12, v198, v190
	ds_bpermute_b32 v13, v198, v191
	ds_bpermute_b32 v14, v198, v192
	ds_bpermute_b32 v15, v198, v193
	ds_bpermute_b32 v16, v198, v194
	ds_bpermute_b32 v17, v198, v195
	s_waitcnt lgkmcnt(6)
	v_cmp_gt_u64_e64 s[14:15], v[188:189], v[10:11]
	s_waitcnt lgkmcnt(4)
	v_cmp_gt_u64_e64 s[16:17], v[190:191], v[12:13]
	s_waitcnt lgkmcnt(2)
	v_cmp_gt_u64_e64 s[18:19], v[192:193], v[14:15]
	s_waitcnt lgkmcnt(0)
	v_cmp_gt_u64_e64 s[20:21], v[194:195], v[16:17]
	s_xor_b64 s[14:15], s[14:15], s[12:13]
	s_xor_b64 s[16:17], s[16:17], s[12:13]
	s_xor_b64 s[18:19], s[18:19], s[12:13]
	s_xor_b64 s[20:21], s[20:21], s[12:13]
	v_cndmask_b32_e64 v188, v188, v10, s[14:15]
	v_cndmask_b32_e64 v189, v189, v11, s[14:15]
	v_cndmask_b32_e64 v190, v190, v12, s[16:17]
	v_cndmask_b32_e64 v191, v191, v13, s[16:17]
	v_cndmask_b32_e64 v192, v192, v14, s[18:19]
	v_cndmask_b32_e64 v193, v193, v15, s[18:19]
	v_cndmask_b32_e64 v194, v194, v16, s[20:21]
	v_cndmask_b32_e64 v195, v195, v17, s[20:21]
	s_xnor_b64 s[12:13], s[8:9], s[2:3]
	ds_bpermute_b32 v10, v197, v188
	ds_bpermute_b32 v11, v197, v189
	ds_bpermute_b32 v12, v197, v190
	ds_bpermute_b32 v13, v197, v191
	ds_bpermute_b32 v14, v197, v192
	ds_bpermute_b32 v15, v197, v193
	ds_bpermute_b32 v16, v197, v194
	ds_bpermute_b32 v17, v197, v195
	s_waitcnt lgkmcnt(6)
	v_cmp_gt_u64_e64 s[14:15], v[188:189], v[10:11]
	s_waitcnt lgkmcnt(4)
	v_cmp_gt_u64_e64 s[16:17], v[190:191], v[12:13]
	s_waitcnt lgkmcnt(2)
	v_cmp_gt_u64_e64 s[18:19], v[192:193], v[14:15]
	s_waitcnt lgkmcnt(0)
	v_cmp_gt_u64_e64 s[20:21], v[194:195], v[16:17]
	s_xor_b64 s[14:15], s[14:15], s[12:13]
	s_xor_b64 s[16:17], s[16:17], s[12:13]
	s_xor_b64 s[18:19], s[18:19], s[12:13]
	s_xor_b64 s[20:21], s[20:21], s[12:13]
	v_cndmask_b32_e64 v188, v188, v10, s[14:15]
	v_cndmask_b32_e64 v189, v189, v11, s[14:15]
	v_cndmask_b32_e64 v190, v190, v12, s[16:17]
	v_cndmask_b32_e64 v191, v191, v13, s[16:17]
	v_cndmask_b32_e64 v192, v192, v14, s[18:19]
	v_cndmask_b32_e64 v193, v193, v15, s[18:19]
	v_cndmask_b32_e64 v194, v194, v16, s[20:21]
	v_cndmask_b32_e64 v195, v195, v17, s[20:21]
	s_xnor_b64 s[12:13], s[8:9], s[0:1]
	ds_bpermute_b32 v10, v196, v188
	ds_bpermute_b32 v11, v196, v189
	ds_bpermute_b32 v12, v196, v190
	ds_bpermute_b32 v13, v196, v191
	ds_bpermute_b32 v14, v196, v192
	ds_bpermute_b32 v15, v196, v193
	ds_bpermute_b32 v16, v196, v194
	ds_bpermute_b32 v17, v196, v195
	s_waitcnt lgkmcnt(6)
	v_cmp_gt_u64_e64 s[14:15], v[188:189], v[10:11]
	s_waitcnt lgkmcnt(4)
	v_cmp_gt_u64_e64 s[16:17], v[190:191], v[12:13]
	s_waitcnt lgkmcnt(2)
	v_cmp_gt_u64_e64 s[18:19], v[192:193], v[14:15]
	s_waitcnt lgkmcnt(0)
	v_cmp_gt_u64_e64 s[20:21], v[194:195], v[16:17]
	s_xor_b64 s[14:15], s[14:15], s[12:13]
	s_xor_b64 s[16:17], s[16:17], s[12:13]
	s_xor_b64 s[18:19], s[18:19], s[12:13]
	s_xor_b64 s[20:21], s[20:21], s[12:13]
	v_cndmask_b32_e64 v188, v188, v10, s[14:15]
	v_cndmask_b32_e64 v189, v189, v11, s[14:15]
	v_cndmask_b32_e64 v190, v190, v12, s[16:17]
	v_cndmask_b32_e64 v191, v191, v13, s[16:17]
	v_cndmask_b32_e64 v192, v192, v14, s[18:19]
	v_cndmask_b32_e64 v193, v193, v15, s[18:19]
	v_cndmask_b32_e64 v194, v194, v16, s[20:21]
	v_cndmask_b32_e64 v195, v195, v17, s[20:21]
	s_not_b64 s[12:13], s[8:9]
	v_cmp_gt_u64_e64 s[14:15], v[188:189], v[192:193]
	v_cmp_gt_u64_e64 s[16:17], v[190:191], v[194:195]
	s_xor_b64 s[14:15], s[14:15], s[12:13]
	s_xor_b64 s[16:17], s[16:17], s[12:13]
	v_cndmask_b32_e64 v2, v188, v192, s[14:15]
	v_cndmask_b32_e64 v3, v189, v193, s[14:15]
	v_cndmask_b32_e64 v6, v192, v188, s[14:15]
	v_cndmask_b32_e64 v7, v193, v189, s[14:15]
	v_cndmask_b32_e64 v4, v190, v194, s[16:17]
	v_cndmask_b32_e64 v5, v191, v195, s[16:17]
	v_cndmask_b32_e64 v8, v194, v190, s[16:17]
	v_cndmask_b32_e64 v9, v195, v191, s[16:17]
	s_not_b64 s[12:13], s[8:9]
	v_cmp_gt_u64_e64 s[14:15], v[2:3], v[4:5]
	v_cmp_gt_u64_e64 s[16:17], v[6:7], v[8:9]
	s_xor_b64 s[14:15], s[14:15], s[12:13]
	s_xor_b64 s[16:17], s[16:17], s[12:13]
	v_cndmask_b32_e64 v188, v2, v4, s[14:15]
	v_cndmask_b32_e64 v189, v3, v5, s[14:15]
	v_cndmask_b32_e64 v190, v4, v2, s[14:15]
	v_cndmask_b32_e64 v191, v5, v3, s[14:15]
	v_cndmask_b32_e64 v192, v6, v8, s[16:17]
	v_cndmask_b32_e64 v193, v7, v9, s[16:17]
	v_cndmask_b32_e64 v194, v8, v6, s[16:17]
	v_cndmask_b32_e64 v195, v9, v7, s[16:17]
	s_xnor_b64 s[12:13], s[10:11], s[8:9]
	ds_bpermute_b32 v10, v200, v188
	ds_bpermute_b32 v11, v200, v189
	ds_bpermute_b32 v12, v200, v190
	ds_bpermute_b32 v13, v200, v191
	ds_bpermute_b32 v14, v200, v192
	ds_bpermute_b32 v15, v200, v193
	ds_bpermute_b32 v16, v200, v194
	ds_bpermute_b32 v17, v200, v195
	s_waitcnt lgkmcnt(6)
	v_cmp_gt_u64_e64 s[14:15], v[188:189], v[10:11]
	s_waitcnt lgkmcnt(4)
	v_cmp_gt_u64_e64 s[16:17], v[190:191], v[12:13]
	s_waitcnt lgkmcnt(2)
	v_cmp_gt_u64_e64 s[18:19], v[192:193], v[14:15]
	s_waitcnt lgkmcnt(0)
	v_cmp_gt_u64_e64 s[20:21], v[194:195], v[16:17]
	s_xor_b64 s[14:15], s[14:15], s[12:13]
	s_xor_b64 s[16:17], s[16:17], s[12:13]
	s_xor_b64 s[18:19], s[18:19], s[12:13]
	s_xor_b64 s[20:21], s[20:21], s[12:13]
	v_cndmask_b32_e64 v188, v188, v10, s[14:15]
	v_cndmask_b32_e64 v189, v189, v11, s[14:15]
	v_cndmask_b32_e64 v190, v190, v12, s[16:17]
	v_cndmask_b32_e64 v191, v191, v13, s[16:17]
	v_cndmask_b32_e64 v192, v192, v14, s[18:19]
	v_cndmask_b32_e64 v193, v193, v15, s[18:19]
	v_cndmask_b32_e64 v194, v194, v16, s[20:21]
	v_cndmask_b32_e64 v195, v195, v17, s[20:21]
	s_xnor_b64 s[12:13], s[10:11], s[6:7]
	ds_bpermute_b32 v10, v199, v188
	ds_bpermute_b32 v11, v199, v189
	ds_bpermute_b32 v12, v199, v190
	ds_bpermute_b32 v13, v199, v191
	ds_bpermute_b32 v14, v199, v192
	ds_bpermute_b32 v15, v199, v193
	ds_bpermute_b32 v16, v199, v194
	ds_bpermute_b32 v17, v199, v195
	s_waitcnt lgkmcnt(6)
	v_cmp_gt_u64_e64 s[14:15], v[188:189], v[10:11]
	s_waitcnt lgkmcnt(4)
	v_cmp_gt_u64_e64 s[16:17], v[190:191], v[12:13]
	s_waitcnt lgkmcnt(2)
	v_cmp_gt_u64_e64 s[18:19], v[192:193], v[14:15]
	s_waitcnt lgkmcnt(0)
	v_cmp_gt_u64_e64 s[20:21], v[194:195], v[16:17]
	s_xor_b64 s[14:15], s[14:15], s[12:13]
	s_xor_b64 s[16:17], s[16:17], s[12:13]
	s_xor_b64 s[18:19], s[18:19], s[12:13]
	s_xor_b64 s[20:21], s[20:21], s[12:13]
	v_cndmask_b32_e64 v188, v188, v10, s[14:15]
	v_cndmask_b32_e64 v189, v189, v11, s[14:15]
	v_cndmask_b32_e64 v190, v190, v12, s[16:17]
	v_cndmask_b32_e64 v191, v191, v13, s[16:17]
	v_cndmask_b32_e64 v192, v192, v14, s[18:19]
	v_cndmask_b32_e64 v193, v193, v15, s[18:19]
	v_cndmask_b32_e64 v194, v194, v16, s[20:21]
	v_cndmask_b32_e64 v195, v195, v17, s[20:21]
	s_xnor_b64 s[12:13], s[10:11], s[4:5]
	ds_bpermute_b32 v10, v198, v188
	ds_bpermute_b32 v11, v198, v189
	ds_bpermute_b32 v12, v198, v190
	ds_bpermute_b32 v13, v198, v191
	ds_bpermute_b32 v14, v198, v192
	ds_bpermute_b32 v15, v198, v193
	ds_bpermute_b32 v16, v198, v194
	ds_bpermute_b32 v17, v198, v195
	s_waitcnt lgkmcnt(6)
	v_cmp_gt_u64_e64 s[14:15], v[188:189], v[10:11]
	s_waitcnt lgkmcnt(4)
	v_cmp_gt_u64_e64 s[16:17], v[190:191], v[12:13]
	s_waitcnt lgkmcnt(2)
	v_cmp_gt_u64_e64 s[18:19], v[192:193], v[14:15]
	s_waitcnt lgkmcnt(0)
	v_cmp_gt_u64_e64 s[20:21], v[194:195], v[16:17]
	s_xor_b64 s[14:15], s[14:15], s[12:13]
	s_xor_b64 s[16:17], s[16:17], s[12:13]
	s_xor_b64 s[18:19], s[18:19], s[12:13]
	s_xor_b64 s[20:21], s[20:21], s[12:13]
	v_cndmask_b32_e64 v188, v188, v10, s[14:15]
	v_cndmask_b32_e64 v189, v189, v11, s[14:15]
	v_cndmask_b32_e64 v190, v190, v12, s[16:17]
	v_cndmask_b32_e64 v191, v191, v13, s[16:17]
	v_cndmask_b32_e64 v192, v192, v14, s[18:19]
	v_cndmask_b32_e64 v193, v193, v15, s[18:19]
	v_cndmask_b32_e64 v194, v194, v16, s[20:21]
	v_cndmask_b32_e64 v195, v195, v17, s[20:21]
	s_xnor_b64 s[12:13], s[10:11], s[2:3]
	ds_bpermute_b32 v10, v197, v188
	ds_bpermute_b32 v11, v197, v189
	ds_bpermute_b32 v12, v197, v190
	ds_bpermute_b32 v13, v197, v191
	ds_bpermute_b32 v14, v197, v192
	ds_bpermute_b32 v15, v197, v193
	ds_bpermute_b32 v16, v197, v194
	ds_bpermute_b32 v17, v197, v195
	s_waitcnt lgkmcnt(6)
	v_cmp_gt_u64_e64 s[14:15], v[188:189], v[10:11]
	s_waitcnt lgkmcnt(4)
	v_cmp_gt_u64_e64 s[16:17], v[190:191], v[12:13]
	s_waitcnt lgkmcnt(2)
	v_cmp_gt_u64_e64 s[18:19], v[192:193], v[14:15]
	s_waitcnt lgkmcnt(0)
	v_cmp_gt_u64_e64 s[20:21], v[194:195], v[16:17]
	s_xor_b64 s[14:15], s[14:15], s[12:13]
	s_xor_b64 s[16:17], s[16:17], s[12:13]
	s_xor_b64 s[18:19], s[18:19], s[12:13]
	s_xor_b64 s[20:21], s[20:21], s[12:13]
	v_cndmask_b32_e64 v188, v188, v10, s[14:15]
	v_cndmask_b32_e64 v189, v189, v11, s[14:15]
	v_cndmask_b32_e64 v190, v190, v12, s[16:17]
	v_cndmask_b32_e64 v191, v191, v13, s[16:17]
	v_cndmask_b32_e64 v192, v192, v14, s[18:19]
	v_cndmask_b32_e64 v193, v193, v15, s[18:19]
	v_cndmask_b32_e64 v194, v194, v16, s[20:21]
	v_cndmask_b32_e64 v195, v195, v17, s[20:21]
	s_xnor_b64 s[12:13], s[10:11], s[0:1]
	ds_bpermute_b32 v10, v196, v188
	ds_bpermute_b32 v11, v196, v189
	ds_bpermute_b32 v12, v196, v190
	ds_bpermute_b32 v13, v196, v191
	ds_bpermute_b32 v14, v196, v192
	ds_bpermute_b32 v15, v196, v193
	ds_bpermute_b32 v16, v196, v194
	ds_bpermute_b32 v17, v196, v195
	s_waitcnt lgkmcnt(6)
	v_cmp_gt_u64_e64 s[14:15], v[188:189], v[10:11]
	s_waitcnt lgkmcnt(4)
	v_cmp_gt_u64_e64 s[16:17], v[190:191], v[12:13]
	s_waitcnt lgkmcnt(2)
	v_cmp_gt_u64_e64 s[18:19], v[192:193], v[14:15]
	s_waitcnt lgkmcnt(0)
	v_cmp_gt_u64_e64 s[20:21], v[194:195], v[16:17]
	s_xor_b64 s[14:15], s[14:15], s[12:13]
	s_xor_b64 s[16:17], s[16:17], s[12:13]
	s_xor_b64 s[18:19], s[18:19], s[12:13]
	s_xor_b64 s[20:21], s[20:21], s[12:13]
	v_cndmask_b32_e64 v188, v188, v10, s[14:15]
	v_cndmask_b32_e64 v189, v189, v11, s[14:15]
	v_cndmask_b32_e64 v190, v190, v12, s[16:17]
	v_cndmask_b32_e64 v191, v191, v13, s[16:17]
	v_cndmask_b32_e64 v192, v192, v14, s[18:19]
	v_cndmask_b32_e64 v193, v193, v15, s[18:19]
	v_cndmask_b32_e64 v194, v194, v16, s[20:21]
	v_cndmask_b32_e64 v195, v195, v17, s[20:21]
	s_not_b64 s[12:13], s[10:11]
	v_cmp_gt_u64_e64 s[14:15], v[188:189], v[192:193]
	v_cmp_gt_u64_e64 s[16:17], v[190:191], v[194:195]
	s_xor_b64 s[14:15], s[14:15], s[12:13]
	s_xor_b64 s[16:17], s[16:17], s[12:13]
	v_cndmask_b32_e64 v2, v188, v192, s[14:15]
	v_cndmask_b32_e64 v3, v189, v193, s[14:15]
	v_cndmask_b32_e64 v6, v192, v188, s[14:15]
	v_cndmask_b32_e64 v7, v193, v189, s[14:15]
	v_cndmask_b32_e64 v4, v190, v194, s[16:17]
	v_cndmask_b32_e64 v5, v191, v195, s[16:17]
	v_cndmask_b32_e64 v8, v194, v190, s[16:17]
	v_cndmask_b32_e64 v9, v195, v191, s[16:17]
	s_not_b64 s[12:13], s[10:11]
	v_cmp_gt_u64_e64 s[14:15], v[2:3], v[4:5]
	v_cmp_gt_u64_e64 s[16:17], v[6:7], v[8:9]
	s_xor_b64 s[14:15], s[14:15], s[12:13]
	s_xor_b64 s[16:17], s[16:17], s[12:13]
	v_cndmask_b32_e64 v188, v2, v4, s[14:15]
	v_cndmask_b32_e64 v189, v3, v5, s[14:15]
	v_cndmask_b32_e64 v190, v4, v2, s[14:15]
	v_cndmask_b32_e64 v191, v5, v3, s[14:15]
	v_cndmask_b32_e64 v192, v6, v8, s[16:17]
	v_cndmask_b32_e64 v193, v7, v9, s[16:17]
	v_cndmask_b32_e64 v194, v8, v6, s[16:17]
	v_cndmask_b32_e64 v195, v9, v7, s[16:17]
	s_not_b64 s[12:13], s[10:11]
	s_bitcmp1_b32 s22, 0
	s_cselect_b64 s[12:13], s[10:11], s[12:13]
	ds_bpermute_b32 v10, v201, v188
	ds_bpermute_b32 v11, v201, v189
	ds_bpermute_b32 v12, v201, v190
	ds_bpermute_b32 v13, v201, v191
	ds_bpermute_b32 v14, v201, v192
	ds_bpermute_b32 v15, v201, v193
	ds_bpermute_b32 v16, v201, v194
	ds_bpermute_b32 v17, v201, v195
	s_waitcnt lgkmcnt(6)
	v_cmp_gt_u64_e64 s[14:15], v[188:189], v[10:11]
	s_waitcnt lgkmcnt(4)
	v_cmp_gt_u64_e64 s[16:17], v[190:191], v[12:13]
	s_waitcnt lgkmcnt(2)
	v_cmp_gt_u64_e64 s[18:19], v[192:193], v[14:15]
	s_waitcnt lgkmcnt(0)
	v_cmp_gt_u64_e64 s[20:21], v[194:195], v[16:17]
	s_xor_b64 s[14:15], s[14:15], s[12:13]
	s_xor_b64 s[16:17], s[16:17], s[12:13]
	s_xor_b64 s[18:19], s[18:19], s[12:13]
	s_xor_b64 s[20:21], s[20:21], s[12:13]
	v_cndmask_b32_e64 v188, v188, v10, s[14:15]
	v_cndmask_b32_e64 v189, v189, v11, s[14:15]
	v_cndmask_b32_e64 v190, v190, v12, s[16:17]
	v_cndmask_b32_e64 v191, v191, v13, s[16:17]
	v_cndmask_b32_e64 v192, v192, v14, s[18:19]
	v_cndmask_b32_e64 v193, v193, v15, s[18:19]
	v_cndmask_b32_e64 v194, v194, v16, s[20:21]
	v_cndmask_b32_e64 v195, v195, v17, s[20:21]
	s_not_b64 s[12:13], s[8:9]
	s_bitcmp1_b32 s22, 0
	s_cselect_b64 s[12:13], s[8:9], s[12:13]
	ds_bpermute_b32 v10, v200, v188
	ds_bpermute_b32 v11, v200, v189
	ds_bpermute_b32 v12, v200, v190
	ds_bpermute_b32 v13, v200, v191
	ds_bpermute_b32 v14, v200, v192
	ds_bpermute_b32 v15, v200, v193
	ds_bpermute_b32 v16, v200, v194
	ds_bpermute_b32 v17, v200, v195
	s_waitcnt lgkmcnt(6)
	v_cmp_gt_u64_e64 s[14:15], v[188:189], v[10:11]
	s_waitcnt lgkmcnt(4)
	v_cmp_gt_u64_e64 s[16:17], v[190:191], v[12:13]
	s_waitcnt lgkmcnt(2)
	v_cmp_gt_u64_e64 s[18:19], v[192:193], v[14:15]
	s_waitcnt lgkmcnt(0)
	v_cmp_gt_u64_e64 s[20:21], v[194:195], v[16:17]
	s_xor_b64 s[14:15], s[14:15], s[12:13]
	s_xor_b64 s[16:17], s[16:17], s[12:13]
	s_xor_b64 s[18:19], s[18:19], s[12:13]
	s_xor_b64 s[20:21], s[20:21], s[12:13]
	v_cndmask_b32_e64 v188, v188, v10, s[14:15]
	v_cndmask_b32_e64 v189, v189, v11, s[14:15]
	v_cndmask_b32_e64 v190, v190, v12, s[16:17]
	v_cndmask_b32_e64 v191, v191, v13, s[16:17]
	v_cndmask_b32_e64 v192, v192, v14, s[18:19]
	v_cndmask_b32_e64 v193, v193, v15, s[18:19]
	v_cndmask_b32_e64 v194, v194, v16, s[20:21]
	v_cndmask_b32_e64 v195, v195, v17, s[20:21]
	s_not_b64 s[12:13], s[6:7]
	s_bitcmp1_b32 s22, 0
	s_cselect_b64 s[12:13], s[6:7], s[12:13]
	ds_bpermute_b32 v10, v199, v188
	ds_bpermute_b32 v11, v199, v189
	ds_bpermute_b32 v12, v199, v190
	ds_bpermute_b32 v13, v199, v191
	ds_bpermute_b32 v14, v199, v192
	ds_bpermute_b32 v15, v199, v193
	ds_bpermute_b32 v16, v199, v194
	ds_bpermute_b32 v17, v199, v195
	s_waitcnt lgkmcnt(6)
	v_cmp_gt_u64_e64 s[14:15], v[188:189], v[10:11]
	s_waitcnt lgkmcnt(4)
	v_cmp_gt_u64_e64 s[16:17], v[190:191], v[12:13]
	s_waitcnt lgkmcnt(2)
	v_cmp_gt_u64_e64 s[18:19], v[192:193], v[14:15]
	s_waitcnt lgkmcnt(0)
	v_cmp_gt_u64_e64 s[20:21], v[194:195], v[16:17]
	s_xor_b64 s[14:15], s[14:15], s[12:13]
	s_xor_b64 s[16:17], s[16:17], s[12:13]
	s_xor_b64 s[18:19], s[18:19], s[12:13]
	s_xor_b64 s[20:21], s[20:21], s[12:13]
	v_cndmask_b32_e64 v188, v188, v10, s[14:15]
	v_cndmask_b32_e64 v189, v189, v11, s[14:15]
	v_cndmask_b32_e64 v190, v190, v12, s[16:17]
	v_cndmask_b32_e64 v191, v191, v13, s[16:17]
	v_cndmask_b32_e64 v192, v192, v14, s[18:19]
	v_cndmask_b32_e64 v193, v193, v15, s[18:19]
	v_cndmask_b32_e64 v194, v194, v16, s[20:21]
	v_cndmask_b32_e64 v195, v195, v17, s[20:21]
	s_not_b64 s[12:13], s[4:5]
	s_bitcmp1_b32 s22, 0
	s_cselect_b64 s[12:13], s[4:5], s[12:13]
	ds_bpermute_b32 v10, v198, v188
	ds_bpermute_b32 v11, v198, v189
	ds_bpermute_b32 v12, v198, v190
	ds_bpermute_b32 v13, v198, v191
	ds_bpermute_b32 v14, v198, v192
	ds_bpermute_b32 v15, v198, v193
	ds_bpermute_b32 v16, v198, v194
	ds_bpermute_b32 v17, v198, v195
	s_waitcnt lgkmcnt(6)
	v_cmp_gt_u64_e64 s[14:15], v[188:189], v[10:11]
	s_waitcnt lgkmcnt(4)
	v_cmp_gt_u64_e64 s[16:17], v[190:191], v[12:13]
	s_waitcnt lgkmcnt(2)
	v_cmp_gt_u64_e64 s[18:19], v[192:193], v[14:15]
	s_waitcnt lgkmcnt(0)
	v_cmp_gt_u64_e64 s[20:21], v[194:195], v[16:17]
	s_xor_b64 s[14:15], s[14:15], s[12:13]
	s_xor_b64 s[16:17], s[16:17], s[12:13]
	s_xor_b64 s[18:19], s[18:19], s[12:13]
	s_xor_b64 s[20:21], s[20:21], s[12:13]
	v_cndmask_b32_e64 v188, v188, v10, s[14:15]
	v_cndmask_b32_e64 v189, v189, v11, s[14:15]
	v_cndmask_b32_e64 v190, v190, v12, s[16:17]
	v_cndmask_b32_e64 v191, v191, v13, s[16:17]
	v_cndmask_b32_e64 v192, v192, v14, s[18:19]
	v_cndmask_b32_e64 v193, v193, v15, s[18:19]
	v_cndmask_b32_e64 v194, v194, v16, s[20:21]
	v_cndmask_b32_e64 v195, v195, v17, s[20:21]
	s_not_b64 s[12:13], s[2:3]
	s_bitcmp1_b32 s22, 0
	s_cselect_b64 s[12:13], s[2:3], s[12:13]
	ds_bpermute_b32 v10, v197, v188
	ds_bpermute_b32 v11, v197, v189
	ds_bpermute_b32 v12, v197, v190
	ds_bpermute_b32 v13, v197, v191
	ds_bpermute_b32 v14, v197, v192
	ds_bpermute_b32 v15, v197, v193
	ds_bpermute_b32 v16, v197, v194
	ds_bpermute_b32 v17, v197, v195
	s_waitcnt lgkmcnt(6)
	v_cmp_gt_u64_e64 s[14:15], v[188:189], v[10:11]
	s_waitcnt lgkmcnt(4)
	v_cmp_gt_u64_e64 s[16:17], v[190:191], v[12:13]
	s_waitcnt lgkmcnt(2)
	v_cmp_gt_u64_e64 s[18:19], v[192:193], v[14:15]
	s_waitcnt lgkmcnt(0)
	v_cmp_gt_u64_e64 s[20:21], v[194:195], v[16:17]
	s_xor_b64 s[14:15], s[14:15], s[12:13]
	s_xor_b64 s[16:17], s[16:17], s[12:13]
	s_xor_b64 s[18:19], s[18:19], s[12:13]
	s_xor_b64 s[20:21], s[20:21], s[12:13]
	v_cndmask_b32_e64 v188, v188, v10, s[14:15]
	v_cndmask_b32_e64 v189, v189, v11, s[14:15]
	v_cndmask_b32_e64 v190, v190, v12, s[16:17]
	v_cndmask_b32_e64 v191, v191, v13, s[16:17]
	v_cndmask_b32_e64 v192, v192, v14, s[18:19]
	v_cndmask_b32_e64 v193, v193, v15, s[18:19]
	v_cndmask_b32_e64 v194, v194, v16, s[20:21]
	v_cndmask_b32_e64 v195, v195, v17, s[20:21]
	s_not_b64 s[12:13], s[0:1]
	s_bitcmp1_b32 s22, 0
	s_cselect_b64 s[12:13], s[0:1], s[12:13]
	ds_bpermute_b32 v10, v196, v188
	ds_bpermute_b32 v11, v196, v189
	ds_bpermute_b32 v12, v196, v190
	ds_bpermute_b32 v13, v196, v191
	ds_bpermute_b32 v14, v196, v192
	ds_bpermute_b32 v15, v196, v193
	ds_bpermute_b32 v16, v196, v194
	ds_bpermute_b32 v17, v196, v195
	s_waitcnt lgkmcnt(6)
	v_cmp_gt_u64_e64 s[14:15], v[188:189], v[10:11]
	s_waitcnt lgkmcnt(4)
	v_cmp_gt_u64_e64 s[16:17], v[190:191], v[12:13]
	s_waitcnt lgkmcnt(2)
	v_cmp_gt_u64_e64 s[18:19], v[192:193], v[14:15]
	s_waitcnt lgkmcnt(0)
	v_cmp_gt_u64_e64 s[20:21], v[194:195], v[16:17]
	s_xor_b64 s[14:15], s[14:15], s[12:13]
	s_xor_b64 s[16:17], s[16:17], s[12:13]
	s_xor_b64 s[18:19], s[18:19], s[12:13]
	s_xor_b64 s[20:21], s[20:21], s[12:13]
	v_cndmask_b32_e64 v188, v188, v10, s[14:15]
	v_cndmask_b32_e64 v189, v189, v11, s[14:15]
	v_cndmask_b32_e64 v190, v190, v12, s[16:17]
	v_cndmask_b32_e64 v191, v191, v13, s[16:17]
	v_cndmask_b32_e64 v192, v192, v14, s[18:19]
	v_cndmask_b32_e64 v193, v193, v15, s[18:19]
	v_cndmask_b32_e64 v194, v194, v16, s[20:21]
	v_cndmask_b32_e64 v195, v195, v17, s[20:21]
	s_bitcmp0_b32 s22, 0
	s_cselect_b64 s[12:13], -1, 0
	v_cmp_gt_u64_e64 s[14:15], v[188:189], v[192:193]
	v_cmp_gt_u64_e64 s[16:17], v[190:191], v[194:195]
	s_xor_b64 s[14:15], s[14:15], s[12:13]
	s_xor_b64 s[16:17], s[16:17], s[12:13]
	v_cndmask_b32_e64 v2, v188, v192, s[14:15]
	v_cndmask_b32_e64 v3, v189, v193, s[14:15]
	v_cndmask_b32_e64 v6, v192, v188, s[14:15]
	v_cndmask_b32_e64 v7, v193, v189, s[14:15]
	v_cndmask_b32_e64 v4, v190, v194, s[16:17]
	v_cndmask_b32_e64 v5, v191, v195, s[16:17]
	v_cndmask_b32_e64 v8, v194, v190, s[16:17]
	v_cndmask_b32_e64 v9, v195, v191, s[16:17]
	s_bitcmp0_b32 s22, 0
	s_cselect_b64 s[12:13], -1, 0
	v_cmp_gt_u64_e64 s[14:15], v[2:3], v[4:5]
	v_cmp_gt_u64_e64 s[16:17], v[6:7], v[8:9]
	s_xor_b64 s[14:15], s[14:15], s[12:13]
	s_xor_b64 s[16:17], s[16:17], s[12:13]
	v_cndmask_b32_e64 v188, v2, v4, s[14:15]
	v_cndmask_b32_e64 v189, v3, v5, s[14:15]
	v_cndmask_b32_e64 v190, v4, v2, s[14:15]
	v_cndmask_b32_e64 v191, v5, v3, s[14:15]
	v_cndmask_b32_e64 v192, v6, v8, s[16:17]
	v_cndmask_b32_e64 v193, v7, v9, s[16:17]
	v_cndmask_b32_e64 v194, v8, v6, s[16:17]
	v_cndmask_b32_e64 v195, v9, v7, s[16:17]
	s_lshr_b32 s98, s22, 1
	s_lshr_b32 s99, s22, 0
	s_xor_b32 s98, s98, s99
	s_bitcmp0_b32 s98, 0
	s_cselect_b64 s[12:13], -1, 0
	ds_write_b128 v202, v[188:191]
	ds_write_b128 v202, v[192:195] offset:16
	s_waitcnt lgkmcnt(0)
	s_barrier
	ds_read_b128 v[10:13], v203
	ds_read_b128 v[14:17], v203 offset:16
	s_waitcnt lgkmcnt(1)
	v_cmp_gt_u64_e64 s[14:15], v[188:189], v[10:11]
	v_cmp_gt_u64_e64 s[16:17], v[190:191], v[12:13]
	s_waitcnt lgkmcnt(0)
	v_cmp_gt_u64_e64 s[18:19], v[192:193], v[14:15]
	v_cmp_gt_u64_e64 s[20:21], v[194:195], v[16:17]
	s_xor_b64 s[14:15], s[14:15], s[12:13]
	s_xor_b64 s[16:17], s[16:17], s[12:13]
	s_xor_b64 s[18:19], s[18:19], s[12:13]
	s_xor_b64 s[20:21], s[20:21], s[12:13]
	v_cndmask_b32_e64 v188, v188, v10, s[14:15]
	v_cndmask_b32_e64 v189, v189, v11, s[14:15]
	v_cndmask_b32_e64 v190, v190, v12, s[16:17]
	v_cndmask_b32_e64 v191, v191, v13, s[16:17]
	v_cndmask_b32_e64 v192, v192, v14, s[18:19]
	v_cndmask_b32_e64 v193, v193, v15, s[18:19]
	v_cndmask_b32_e64 v194, v194, v16, s[20:21]
	v_cndmask_b32_e64 v195, v195, v17, s[20:21]
	s_not_b64 s[12:13], s[10:11]
	s_bitcmp1_b32 s22, 1
	s_cselect_b64 s[12:13], s[10:11], s[12:13]
	ds_bpermute_b32 v10, v201, v188
	ds_bpermute_b32 v11, v201, v189
	ds_bpermute_b32 v12, v201, v190
	ds_bpermute_b32 v13, v201, v191
	ds_bpermute_b32 v14, v201, v192
	ds_bpermute_b32 v15, v201, v193
	ds_bpermute_b32 v16, v201, v194
	ds_bpermute_b32 v17, v201, v195
	s_waitcnt lgkmcnt(6)
	v_cmp_gt_u64_e64 s[14:15], v[188:189], v[10:11]
	s_waitcnt lgkmcnt(4)
	v_cmp_gt_u64_e64 s[16:17], v[190:191], v[12:13]
	s_waitcnt lgkmcnt(2)
	v_cmp_gt_u64_e64 s[18:19], v[192:193], v[14:15]
	s_waitcnt lgkmcnt(0)
	v_cmp_gt_u64_e64 s[20:21], v[194:195], v[16:17]
	s_xor_b64 s[14:15], s[14:15], s[12:13]
	s_xor_b64 s[16:17], s[16:17], s[12:13]
	s_xor_b64 s[18:19], s[18:19], s[12:13]
	s_xor_b64 s[20:21], s[20:21], s[12:13]
	v_cndmask_b32_e64 v188, v188, v10, s[14:15]
	v_cndmask_b32_e64 v189, v189, v11, s[14:15]
	v_cndmask_b32_e64 v190, v190, v12, s[16:17]
	v_cndmask_b32_e64 v191, v191, v13, s[16:17]
	v_cndmask_b32_e64 v192, v192, v14, s[18:19]
	v_cndmask_b32_e64 v193, v193, v15, s[18:19]
	v_cndmask_b32_e64 v194, v194, v16, s[20:21]
	v_cndmask_b32_e64 v195, v195, v17, s[20:21]
	s_not_b64 s[12:13], s[8:9]
	s_bitcmp1_b32 s22, 1
	s_cselect_b64 s[12:13], s[8:9], s[12:13]
	ds_bpermute_b32 v10, v200, v188
	ds_bpermute_b32 v11, v200, v189
	ds_bpermute_b32 v12, v200, v190
	ds_bpermute_b32 v13, v200, v191
	ds_bpermute_b32 v14, v200, v192
	ds_bpermute_b32 v15, v200, v193
	ds_bpermute_b32 v16, v200, v194
	ds_bpermute_b32 v17, v200, v195
	s_waitcnt lgkmcnt(6)
	v_cmp_gt_u64_e64 s[14:15], v[188:189], v[10:11]
	s_waitcnt lgkmcnt(4)
	v_cmp_gt_u64_e64 s[16:17], v[190:191], v[12:13]
	s_waitcnt lgkmcnt(2)
	v_cmp_gt_u64_e64 s[18:19], v[192:193], v[14:15]
	s_waitcnt lgkmcnt(0)
	v_cmp_gt_u64_e64 s[20:21], v[194:195], v[16:17]
	s_xor_b64 s[14:15], s[14:15], s[12:13]
	s_xor_b64 s[16:17], s[16:17], s[12:13]
	s_xor_b64 s[18:19], s[18:19], s[12:13]
	s_xor_b64 s[20:21], s[20:21], s[12:13]
	v_cndmask_b32_e64 v188, v188, v10, s[14:15]
	v_cndmask_b32_e64 v189, v189, v11, s[14:15]
	v_cndmask_b32_e64 v190, v190, v12, s[16:17]
	v_cndmask_b32_e64 v191, v191, v13, s[16:17]
	v_cndmask_b32_e64 v192, v192, v14, s[18:19]
	v_cndmask_b32_e64 v193, v193, v15, s[18:19]
	v_cndmask_b32_e64 v194, v194, v16, s[20:21]
	v_cndmask_b32_e64 v195, v195, v17, s[20:21]
	s_not_b64 s[12:13], s[6:7]
	s_bitcmp1_b32 s22, 1
	s_cselect_b64 s[12:13], s[6:7], s[12:13]
	ds_bpermute_b32 v10, v199, v188
	ds_bpermute_b32 v11, v199, v189
	ds_bpermute_b32 v12, v199, v190
	ds_bpermute_b32 v13, v199, v191
	ds_bpermute_b32 v14, v199, v192
	ds_bpermute_b32 v15, v199, v193
	ds_bpermute_b32 v16, v199, v194
	ds_bpermute_b32 v17, v199, v195
	s_waitcnt lgkmcnt(6)
	v_cmp_gt_u64_e64 s[14:15], v[188:189], v[10:11]
	s_waitcnt lgkmcnt(4)
	v_cmp_gt_u64_e64 s[16:17], v[190:191], v[12:13]
	s_waitcnt lgkmcnt(2)
	v_cmp_gt_u64_e64 s[18:19], v[192:193], v[14:15]
	s_waitcnt lgkmcnt(0)
	v_cmp_gt_u64_e64 s[20:21], v[194:195], v[16:17]
	s_xor_b64 s[14:15], s[14:15], s[12:13]
	s_xor_b64 s[16:17], s[16:17], s[12:13]
	s_xor_b64 s[18:19], s[18:19], s[12:13]
	s_xor_b64 s[20:21], s[20:21], s[12:13]
	v_cndmask_b32_e64 v188, v188, v10, s[14:15]
	v_cndmask_b32_e64 v189, v189, v11, s[14:15]
	v_cndmask_b32_e64 v190, v190, v12, s[16:17]
	v_cndmask_b32_e64 v191, v191, v13, s[16:17]
	v_cndmask_b32_e64 v192, v192, v14, s[18:19]
	v_cndmask_b32_e64 v193, v193, v15, s[18:19]
	v_cndmask_b32_e64 v194, v194, v16, s[20:21]
	v_cndmask_b32_e64 v195, v195, v17, s[20:21]
	s_not_b64 s[12:13], s[4:5]
	s_bitcmp1_b32 s22, 1
	s_cselect_b64 s[12:13], s[4:5], s[12:13]
	ds_bpermute_b32 v10, v198, v188
	ds_bpermute_b32 v11, v198, v189
	ds_bpermute_b32 v12, v198, v190
	ds_bpermute_b32 v13, v198, v191
	ds_bpermute_b32 v14, v198, v192
	ds_bpermute_b32 v15, v198, v193
	ds_bpermute_b32 v16, v198, v194
	ds_bpermute_b32 v17, v198, v195
	s_waitcnt lgkmcnt(6)
	v_cmp_gt_u64_e64 s[14:15], v[188:189], v[10:11]
	s_waitcnt lgkmcnt(4)
	v_cmp_gt_u64_e64 s[16:17], v[190:191], v[12:13]
	s_waitcnt lgkmcnt(2)
	v_cmp_gt_u64_e64 s[18:19], v[192:193], v[14:15]
	s_waitcnt lgkmcnt(0)
	v_cmp_gt_u64_e64 s[20:21], v[194:195], v[16:17]
	s_xor_b64 s[14:15], s[14:15], s[12:13]
	s_xor_b64 s[16:17], s[16:17], s[12:13]
	s_xor_b64 s[18:19], s[18:19], s[12:13]
	s_xor_b64 s[20:21], s[20:21], s[12:13]
	v_cndmask_b32_e64 v188, v188, v10, s[14:15]
	v_cndmask_b32_e64 v189, v189, v11, s[14:15]
	v_cndmask_b32_e64 v190, v190, v12, s[16:17]
	v_cndmask_b32_e64 v191, v191, v13, s[16:17]
	v_cndmask_b32_e64 v192, v192, v14, s[18:19]
	v_cndmask_b32_e64 v193, v193, v15, s[18:19]
	v_cndmask_b32_e64 v194, v194, v16, s[20:21]
	v_cndmask_b32_e64 v195, v195, v17, s[20:21]
	s_not_b64 s[12:13], s[2:3]
	s_bitcmp1_b32 s22, 1
	s_cselect_b64 s[12:13], s[2:3], s[12:13]
	ds_bpermute_b32 v10, v197, v188
	ds_bpermute_b32 v11, v197, v189
	ds_bpermute_b32 v12, v197, v190
	ds_bpermute_b32 v13, v197, v191
	ds_bpermute_b32 v14, v197, v192
	ds_bpermute_b32 v15, v197, v193
	ds_bpermute_b32 v16, v197, v194
	ds_bpermute_b32 v17, v197, v195
	s_waitcnt lgkmcnt(6)
	v_cmp_gt_u64_e64 s[14:15], v[188:189], v[10:11]
	s_waitcnt lgkmcnt(4)
	v_cmp_gt_u64_e64 s[16:17], v[190:191], v[12:13]
	s_waitcnt lgkmcnt(2)
	v_cmp_gt_u64_e64 s[18:19], v[192:193], v[14:15]
	s_waitcnt lgkmcnt(0)
	v_cmp_gt_u64_e64 s[20:21], v[194:195], v[16:17]
	s_xor_b64 s[14:15], s[14:15], s[12:13]
	s_xor_b64 s[16:17], s[16:17], s[12:13]
	s_xor_b64 s[18:19], s[18:19], s[12:13]
	s_xor_b64 s[20:21], s[20:21], s[12:13]
	v_cndmask_b32_e64 v188, v188, v10, s[14:15]
	v_cndmask_b32_e64 v189, v189, v11, s[14:15]
	v_cndmask_b32_e64 v190, v190, v12, s[16:17]
	v_cndmask_b32_e64 v191, v191, v13, s[16:17]
	v_cndmask_b32_e64 v192, v192, v14, s[18:19]
	v_cndmask_b32_e64 v193, v193, v15, s[18:19]
	v_cndmask_b32_e64 v194, v194, v16, s[20:21]
	v_cndmask_b32_e64 v195, v195, v17, s[20:21]
	s_not_b64 s[12:13], s[0:1]
	s_bitcmp1_b32 s22, 1
	s_cselect_b64 s[12:13], s[0:1], s[12:13]
	ds_bpermute_b32 v10, v196, v188
	ds_bpermute_b32 v11, v196, v189
	ds_bpermute_b32 v12, v196, v190
	ds_bpermute_b32 v13, v196, v191
	ds_bpermute_b32 v14, v196, v192
	ds_bpermute_b32 v15, v196, v193
	ds_bpermute_b32 v16, v196, v194
	ds_bpermute_b32 v17, v196, v195
	s_waitcnt lgkmcnt(6)
	v_cmp_gt_u64_e64 s[14:15], v[188:189], v[10:11]
	s_waitcnt lgkmcnt(4)
	v_cmp_gt_u64_e64 s[16:17], v[190:191], v[12:13]
	s_waitcnt lgkmcnt(2)
	v_cmp_gt_u64_e64 s[18:19], v[192:193], v[14:15]
	s_waitcnt lgkmcnt(0)
	v_cmp_gt_u64_e64 s[20:21], v[194:195], v[16:17]
	s_xor_b64 s[14:15], s[14:15], s[12:13]
	s_xor_b64 s[16:17], s[16:17], s[12:13]
	s_xor_b64 s[18:19], s[18:19], s[12:13]
	s_xor_b64 s[20:21], s[20:21], s[12:13]
	v_cndmask_b32_e64 v188, v188, v10, s[14:15]
	v_cndmask_b32_e64 v189, v189, v11, s[14:15]
	v_cndmask_b32_e64 v190, v190, v12, s[16:17]
	v_cndmask_b32_e64 v191, v191, v13, s[16:17]
	v_cndmask_b32_e64 v192, v192, v14, s[18:19]
	v_cndmask_b32_e64 v193, v193, v15, s[18:19]
	v_cndmask_b32_e64 v194, v194, v16, s[20:21]
	v_cndmask_b32_e64 v195, v195, v17, s[20:21]
	s_bitcmp0_b32 s22, 1
	s_cselect_b64 s[12:13], -1, 0
	v_cmp_gt_u64_e64 s[14:15], v[188:189], v[192:193]
	v_cmp_gt_u64_e64 s[16:17], v[190:191], v[194:195]
	s_xor_b64 s[14:15], s[14:15], s[12:13]
	s_xor_b64 s[16:17], s[16:17], s[12:13]
	v_cndmask_b32_e64 v2, v188, v192, s[14:15]
	v_cndmask_b32_e64 v3, v189, v193, s[14:15]
	v_cndmask_b32_e64 v6, v192, v188, s[14:15]
	v_cndmask_b32_e64 v7, v193, v189, s[14:15]
	v_cndmask_b32_e64 v4, v190, v194, s[16:17]
	v_cndmask_b32_e64 v5, v191, v195, s[16:17]
	v_cndmask_b32_e64 v8, v194, v190, s[16:17]
	v_cndmask_b32_e64 v9, v195, v191, s[16:17]
	s_bitcmp0_b32 s22, 1
	s_cselect_b64 s[12:13], -1, 0
	v_cmp_gt_u64_e64 s[14:15], v[2:3], v[4:5]
	v_cmp_gt_u64_e64 s[16:17], v[6:7], v[8:9]
	s_xor_b64 s[14:15], s[14:15], s[12:13]
	s_xor_b64 s[16:17], s[16:17], s[12:13]
	v_cndmask_b32_e64 v188, v2, v4, s[14:15]
	v_cndmask_b32_e64 v189, v3, v5, s[14:15]
	v_cndmask_b32_e64 v190, v4, v2, s[14:15]
	v_cndmask_b32_e64 v191, v5, v3, s[14:15]
	v_cndmask_b32_e64 v192, v6, v8, s[16:17]
	v_cndmask_b32_e64 v193, v7, v9, s[16:17]
	v_cndmask_b32_e64 v194, v8, v6, s[16:17]
	v_cndmask_b32_e64 v195, v9, v7, s[16:17]
	s_lshr_b32 s98, s22, 2
	s_lshr_b32 s99, s22, 1
	s_xor_b32 s98, s98, s99
	s_bitcmp0_b32 s98, 0
	s_cselect_b64 s[12:13], -1, 0
	ds_write_b128 v202, v[188:191] offset:16384
	ds_write_b128 v202, v[192:195] offset:16400
	s_waitcnt lgkmcnt(0)
	s_barrier
	ds_read_b128 v[10:13], v204 offset:16384
	ds_read_b128 v[14:17], v204 offset:16400
	s_waitcnt lgkmcnt(1)
	v_cmp_gt_u64_e64 s[14:15], v[188:189], v[10:11]
	v_cmp_gt_u64_e64 s[16:17], v[190:191], v[12:13]
	s_waitcnt lgkmcnt(0)
	v_cmp_gt_u64_e64 s[18:19], v[192:193], v[14:15]
	v_cmp_gt_u64_e64 s[20:21], v[194:195], v[16:17]
	s_xor_b64 s[14:15], s[14:15], s[12:13]
	s_xor_b64 s[16:17], s[16:17], s[12:13]
	s_xor_b64 s[18:19], s[18:19], s[12:13]
	s_xor_b64 s[20:21], s[20:21], s[12:13]
	v_cndmask_b32_e64 v188, v188, v10, s[14:15]
	v_cndmask_b32_e64 v189, v189, v11, s[14:15]
	v_cndmask_b32_e64 v190, v190, v12, s[16:17]
	v_cndmask_b32_e64 v191, v191, v13, s[16:17]
	v_cndmask_b32_e64 v192, v192, v14, s[18:19]
	v_cndmask_b32_e64 v193, v193, v15, s[18:19]
	v_cndmask_b32_e64 v194, v194, v16, s[20:21]
	v_cndmask_b32_e64 v195, v195, v17, s[20:21]
	s_lshr_b32 s98, s22, 2
	s_lshr_b32 s99, s22, 0
	s_xor_b32 s98, s98, s99
	s_bitcmp0_b32 s98, 0
	s_cselect_b64 s[12:13], -1, 0
	ds_write_b128 v202, v[188:191]
	ds_write_b128 v202, v[192:195] offset:16
	s_waitcnt lgkmcnt(0)
	s_barrier
	ds_read_b128 v[10:13], v203
	ds_read_b128 v[14:17], v203 offset:16
	s_waitcnt lgkmcnt(1)
	v_cmp_gt_u64_e64 s[14:15], v[188:189], v[10:11]
	v_cmp_gt_u64_e64 s[16:17], v[190:191], v[12:13]
	s_waitcnt lgkmcnt(0)
	v_cmp_gt_u64_e64 s[18:19], v[192:193], v[14:15]
	v_cmp_gt_u64_e64 s[20:21], v[194:195], v[16:17]
	s_xor_b64 s[14:15], s[14:15], s[12:13]
	s_xor_b64 s[16:17], s[16:17], s[12:13]
	s_xor_b64 s[18:19], s[18:19], s[12:13]
	s_xor_b64 s[20:21], s[20:21], s[12:13]
	v_cndmask_b32_e64 v188, v188, v10, s[14:15]
	v_cndmask_b32_e64 v189, v189, v11, s[14:15]
	v_cndmask_b32_e64 v190, v190, v12, s[16:17]
	v_cndmask_b32_e64 v191, v191, v13, s[16:17]
	v_cndmask_b32_e64 v192, v192, v14, s[18:19]
	v_cndmask_b32_e64 v193, v193, v15, s[18:19]
	v_cndmask_b32_e64 v194, v194, v16, s[20:21]
	v_cndmask_b32_e64 v195, v195, v17, s[20:21]
	s_not_b64 s[12:13], s[10:11]
	s_bitcmp1_b32 s22, 2
	s_cselect_b64 s[12:13], s[10:11], s[12:13]
	ds_bpermute_b32 v10, v201, v188
	ds_bpermute_b32 v11, v201, v189
	ds_bpermute_b32 v12, v201, v190
	ds_bpermute_b32 v13, v201, v191
	ds_bpermute_b32 v14, v201, v192
	ds_bpermute_b32 v15, v201, v193
	ds_bpermute_b32 v16, v201, v194
	ds_bpermute_b32 v17, v201, v195
	s_waitcnt lgkmcnt(6)
	v_cmp_gt_u64_e64 s[14:15], v[188:189], v[10:11]
	s_waitcnt lgkmcnt(4)
	v_cmp_gt_u64_e64 s[16:17], v[190:191], v[12:13]
	s_waitcnt lgkmcnt(2)
	v_cmp_gt_u64_e64 s[18:19], v[192:193], v[14:15]
	s_waitcnt lgkmcnt(0)
	v_cmp_gt_u64_e64 s[20:21], v[194:195], v[16:17]
	s_xor_b64 s[14:15], s[14:15], s[12:13]
	s_xor_b64 s[16:17], s[16:17], s[12:13]
	s_xor_b64 s[18:19], s[18:19], s[12:13]
	s_xor_b64 s[20:21], s[20:21], s[12:13]
	v_cndmask_b32_e64 v188, v188, v10, s[14:15]
	v_cndmask_b32_e64 v189, v189, v11, s[14:15]
	v_cndmask_b32_e64 v190, v190, v12, s[16:17]
	v_cndmask_b32_e64 v191, v191, v13, s[16:17]
	v_cndmask_b32_e64 v192, v192, v14, s[18:19]
	v_cndmask_b32_e64 v193, v193, v15, s[18:19]
	v_cndmask_b32_e64 v194, v194, v16, s[20:21]
	v_cndmask_b32_e64 v195, v195, v17, s[20:21]
	s_not_b64 s[12:13], s[8:9]
	s_bitcmp1_b32 s22, 2
	s_cselect_b64 s[12:13], s[8:9], s[12:13]
	ds_bpermute_b32 v10, v200, v188
	ds_bpermute_b32 v11, v200, v189
	ds_bpermute_b32 v12, v200, v190
	ds_bpermute_b32 v13, v200, v191
	ds_bpermute_b32 v14, v200, v192
	ds_bpermute_b32 v15, v200, v193
	ds_bpermute_b32 v16, v200, v194
	ds_bpermute_b32 v17, v200, v195
	s_waitcnt lgkmcnt(6)
	v_cmp_gt_u64_e64 s[14:15], v[188:189], v[10:11]
	s_waitcnt lgkmcnt(4)
	v_cmp_gt_u64_e64 s[16:17], v[190:191], v[12:13]
	s_waitcnt lgkmcnt(2)
	v_cmp_gt_u64_e64 s[18:19], v[192:193], v[14:15]
	s_waitcnt lgkmcnt(0)
	v_cmp_gt_u64_e64 s[20:21], v[194:195], v[16:17]
	s_xor_b64 s[14:15], s[14:15], s[12:13]
	s_xor_b64 s[16:17], s[16:17], s[12:13]
	s_xor_b64 s[18:19], s[18:19], s[12:13]
	s_xor_b64 s[20:21], s[20:21], s[12:13]
	v_cndmask_b32_e64 v188, v188, v10, s[14:15]
	v_cndmask_b32_e64 v189, v189, v11, s[14:15]
	v_cndmask_b32_e64 v190, v190, v12, s[16:17]
	v_cndmask_b32_e64 v191, v191, v13, s[16:17]
	v_cndmask_b32_e64 v192, v192, v14, s[18:19]
	v_cndmask_b32_e64 v193, v193, v15, s[18:19]
	v_cndmask_b32_e64 v194, v194, v16, s[20:21]
	v_cndmask_b32_e64 v195, v195, v17, s[20:21]
	s_not_b64 s[12:13], s[6:7]
	s_bitcmp1_b32 s22, 2
	s_cselect_b64 s[12:13], s[6:7], s[12:13]
	ds_bpermute_b32 v10, v199, v188
	ds_bpermute_b32 v11, v199, v189
	ds_bpermute_b32 v12, v199, v190
	ds_bpermute_b32 v13, v199, v191
	ds_bpermute_b32 v14, v199, v192
	ds_bpermute_b32 v15, v199, v193
	ds_bpermute_b32 v16, v199, v194
	ds_bpermute_b32 v17, v199, v195
	s_waitcnt lgkmcnt(6)
	v_cmp_gt_u64_e64 s[14:15], v[188:189], v[10:11]
	s_waitcnt lgkmcnt(4)
	v_cmp_gt_u64_e64 s[16:17], v[190:191], v[12:13]
	s_waitcnt lgkmcnt(2)
	v_cmp_gt_u64_e64 s[18:19], v[192:193], v[14:15]
	s_waitcnt lgkmcnt(0)
	v_cmp_gt_u64_e64 s[20:21], v[194:195], v[16:17]
	s_xor_b64 s[14:15], s[14:15], s[12:13]
	s_xor_b64 s[16:17], s[16:17], s[12:13]
	s_xor_b64 s[18:19], s[18:19], s[12:13]
	s_xor_b64 s[20:21], s[20:21], s[12:13]
	v_cndmask_b32_e64 v188, v188, v10, s[14:15]
	v_cndmask_b32_e64 v189, v189, v11, s[14:15]
	v_cndmask_b32_e64 v190, v190, v12, s[16:17]
	v_cndmask_b32_e64 v191, v191, v13, s[16:17]
	v_cndmask_b32_e64 v192, v192, v14, s[18:19]
	v_cndmask_b32_e64 v193, v193, v15, s[18:19]
	v_cndmask_b32_e64 v194, v194, v16, s[20:21]
	v_cndmask_b32_e64 v195, v195, v17, s[20:21]
	s_not_b64 s[12:13], s[4:5]
	s_bitcmp1_b32 s22, 2
	s_cselect_b64 s[12:13], s[4:5], s[12:13]
	ds_bpermute_b32 v10, v198, v188
	ds_bpermute_b32 v11, v198, v189
	ds_bpermute_b32 v12, v198, v190
	ds_bpermute_b32 v13, v198, v191
	ds_bpermute_b32 v14, v198, v192
	ds_bpermute_b32 v15, v198, v193
	ds_bpermute_b32 v16, v198, v194
	ds_bpermute_b32 v17, v198, v195
	s_waitcnt lgkmcnt(6)
	v_cmp_gt_u64_e64 s[14:15], v[188:189], v[10:11]
	s_waitcnt lgkmcnt(4)
	v_cmp_gt_u64_e64 s[16:17], v[190:191], v[12:13]
	s_waitcnt lgkmcnt(2)
	v_cmp_gt_u64_e64 s[18:19], v[192:193], v[14:15]
	s_waitcnt lgkmcnt(0)
	v_cmp_gt_u64_e64 s[20:21], v[194:195], v[16:17]
	s_xor_b64 s[14:15], s[14:15], s[12:13]
	s_xor_b64 s[16:17], s[16:17], s[12:13]
	s_xor_b64 s[18:19], s[18:19], s[12:13]
	s_xor_b64 s[20:21], s[20:21], s[12:13]
	v_cndmask_b32_e64 v188, v188, v10, s[14:15]
	v_cndmask_b32_e64 v189, v189, v11, s[14:15]
	v_cndmask_b32_e64 v190, v190, v12, s[16:17]
	v_cndmask_b32_e64 v191, v191, v13, s[16:17]
	v_cndmask_b32_e64 v192, v192, v14, s[18:19]
	v_cndmask_b32_e64 v193, v193, v15, s[18:19]
	v_cndmask_b32_e64 v194, v194, v16, s[20:21]
	v_cndmask_b32_e64 v195, v195, v17, s[20:21]
	s_not_b64 s[12:13], s[2:3]
	s_bitcmp1_b32 s22, 2
	s_cselect_b64 s[12:13], s[2:3], s[12:13]
	ds_bpermute_b32 v10, v197, v188
	ds_bpermute_b32 v11, v197, v189
	ds_bpermute_b32 v12, v197, v190
	ds_bpermute_b32 v13, v197, v191
	ds_bpermute_b32 v14, v197, v192
	ds_bpermute_b32 v15, v197, v193
	ds_bpermute_b32 v16, v197, v194
	ds_bpermute_b32 v17, v197, v195
	s_waitcnt lgkmcnt(6)
	v_cmp_gt_u64_e64 s[14:15], v[188:189], v[10:11]
	s_waitcnt lgkmcnt(4)
	v_cmp_gt_u64_e64 s[16:17], v[190:191], v[12:13]
	s_waitcnt lgkmcnt(2)
	v_cmp_gt_u64_e64 s[18:19], v[192:193], v[14:15]
	s_waitcnt lgkmcnt(0)
	v_cmp_gt_u64_e64 s[20:21], v[194:195], v[16:17]
	s_xor_b64 s[14:15], s[14:15], s[12:13]
	s_xor_b64 s[16:17], s[16:17], s[12:13]
	s_xor_b64 s[18:19], s[18:19], s[12:13]
	s_xor_b64 s[20:21], s[20:21], s[12:13]
	v_cndmask_b32_e64 v188, v188, v10, s[14:15]
	v_cndmask_b32_e64 v189, v189, v11, s[14:15]
	v_cndmask_b32_e64 v190, v190, v12, s[16:17]
	v_cndmask_b32_e64 v191, v191, v13, s[16:17]
	v_cndmask_b32_e64 v192, v192, v14, s[18:19]
	v_cndmask_b32_e64 v193, v193, v15, s[18:19]
	v_cndmask_b32_e64 v194, v194, v16, s[20:21]
	v_cndmask_b32_e64 v195, v195, v17, s[20:21]
	s_not_b64 s[12:13], s[0:1]
	s_bitcmp1_b32 s22, 2
	s_cselect_b64 s[12:13], s[0:1], s[12:13]
	ds_bpermute_b32 v10, v196, v188
	ds_bpermute_b32 v11, v196, v189
	ds_bpermute_b32 v12, v196, v190
	ds_bpermute_b32 v13, v196, v191
	ds_bpermute_b32 v14, v196, v192
	ds_bpermute_b32 v15, v196, v193
	ds_bpermute_b32 v16, v196, v194
	ds_bpermute_b32 v17, v196, v195
	s_waitcnt lgkmcnt(6)
	v_cmp_gt_u64_e64 s[14:15], v[188:189], v[10:11]
	s_waitcnt lgkmcnt(4)
	v_cmp_gt_u64_e64 s[16:17], v[190:191], v[12:13]
	s_waitcnt lgkmcnt(2)
	v_cmp_gt_u64_e64 s[18:19], v[192:193], v[14:15]
	s_waitcnt lgkmcnt(0)
	v_cmp_gt_u64_e64 s[20:21], v[194:195], v[16:17]
	s_xor_b64 s[14:15], s[14:15], s[12:13]
	s_xor_b64 s[16:17], s[16:17], s[12:13]
	s_xor_b64 s[18:19], s[18:19], s[12:13]
	s_xor_b64 s[20:21], s[20:21], s[12:13]
	v_cndmask_b32_e64 v188, v188, v10, s[14:15]
	v_cndmask_b32_e64 v189, v189, v11, s[14:15]
	v_cndmask_b32_e64 v190, v190, v12, s[16:17]
	v_cndmask_b32_e64 v191, v191, v13, s[16:17]
	v_cndmask_b32_e64 v192, v192, v14, s[18:19]
	v_cndmask_b32_e64 v193, v193, v15, s[18:19]
	v_cndmask_b32_e64 v194, v194, v16, s[20:21]
	v_cndmask_b32_e64 v195, v195, v17, s[20:21]
	s_bitcmp0_b32 s22, 2
	s_cselect_b64 s[12:13], -1, 0
	v_cmp_gt_u64_e64 s[14:15], v[188:189], v[192:193]
	v_cmp_gt_u64_e64 s[16:17], v[190:191], v[194:195]
	s_xor_b64 s[14:15], s[14:15], s[12:13]
	s_xor_b64 s[16:17], s[16:17], s[12:13]
	v_cndmask_b32_e64 v2, v188, v192, s[14:15]
	v_cndmask_b32_e64 v3, v189, v193, s[14:15]
	v_cndmask_b32_e64 v6, v192, v188, s[14:15]
	v_cndmask_b32_e64 v7, v193, v189, s[14:15]
	v_cndmask_b32_e64 v4, v190, v194, s[16:17]
	v_cndmask_b32_e64 v5, v191, v195, s[16:17]
	v_cndmask_b32_e64 v8, v194, v190, s[16:17]
	v_cndmask_b32_e64 v9, v195, v191, s[16:17]
	s_bitcmp0_b32 s22, 2
	s_cselect_b64 s[12:13], -1, 0
	v_cmp_gt_u64_e64 s[14:15], v[2:3], v[4:5]
	v_cmp_gt_u64_e64 s[16:17], v[6:7], v[8:9]
	s_xor_b64 s[14:15], s[14:15], s[12:13]
	s_xor_b64 s[16:17], s[16:17], s[12:13]
	v_cndmask_b32_e64 v188, v2, v4, s[14:15]
	v_cndmask_b32_e64 v189, v3, v5, s[14:15]
	v_cndmask_b32_e64 v190, v4, v2, s[14:15]
	v_cndmask_b32_e64 v191, v5, v3, s[14:15]
	v_cndmask_b32_e64 v192, v6, v8, s[16:17]
	v_cndmask_b32_e64 v193, v7, v9, s[16:17]
	v_cndmask_b32_e64 v194, v8, v6, s[16:17]
	v_cndmask_b32_e64 v195, v9, v7, s[16:17]
	s_bitcmp0_b32 s22, 2
	s_cselect_b64 s[12:13], -1, 0
	ds_write_b128 v202, v[188:191] offset:16384
	ds_write_b128 v202, v[192:195] offset:16400
	s_waitcnt lgkmcnt(0)
	s_barrier
	ds_read_b128 v[10:13], v205 offset:16384
	ds_read_b128 v[14:17], v205 offset:16400
	s_waitcnt lgkmcnt(1)
	v_cmp_gt_u64_e64 s[14:15], v[188:189], v[10:11]
	v_cmp_gt_u64_e64 s[16:17], v[190:191], v[12:13]
	s_waitcnt lgkmcnt(0)
	v_cmp_gt_u64_e64 s[18:19], v[192:193], v[14:15]
	v_cmp_gt_u64_e64 s[20:21], v[194:195], v[16:17]
	s_xor_b64 s[14:15], s[14:15], s[12:13]
	s_xor_b64 s[16:17], s[16:17], s[12:13]
	s_xor_b64 s[18:19], s[18:19], s[12:13]
	s_xor_b64 s[20:21], s[20:21], s[12:13]
	v_cndmask_b32_e64 v188, v188, v10, s[14:15]
	v_cndmask_b32_e64 v189, v189, v11, s[14:15]
	v_cndmask_b32_e64 v190, v190, v12, s[16:17]
	v_cndmask_b32_e64 v191, v191, v13, s[16:17]
	v_cndmask_b32_e64 v192, v192, v14, s[18:19]
	v_cndmask_b32_e64 v193, v193, v15, s[18:19]
	v_cndmask_b32_e64 v194, v194, v16, s[20:21]
	v_cndmask_b32_e64 v195, v195, v17, s[20:21]
	s_bitcmp0_b32 s22, 1
	s_cselect_b64 s[12:13], -1, 0
	ds_write_b128 v202, v[188:191]
	ds_write_b128 v202, v[192:195] offset:16
	s_waitcnt lgkmcnt(0)
	s_barrier
	ds_read_b128 v[10:13], v204
	ds_read_b128 v[14:17], v204 offset:16
	s_waitcnt lgkmcnt(1)
	v_cmp_gt_u64_e64 s[14:15], v[188:189], v[10:11]
	v_cmp_gt_u64_e64 s[16:17], v[190:191], v[12:13]
	s_waitcnt lgkmcnt(0)
	v_cmp_gt_u64_e64 s[18:19], v[192:193], v[14:15]
	v_cmp_gt_u64_e64 s[20:21], v[194:195], v[16:17]
	s_xor_b64 s[14:15], s[14:15], s[12:13]
	s_xor_b64 s[16:17], s[16:17], s[12:13]
	s_xor_b64 s[18:19], s[18:19], s[12:13]
	s_xor_b64 s[20:21], s[20:21], s[12:13]
	v_cndmask_b32_e64 v188, v188, v10, s[14:15]
	v_cndmask_b32_e64 v189, v189, v11, s[14:15]
	v_cndmask_b32_e64 v190, v190, v12, s[16:17]
	v_cndmask_b32_e64 v191, v191, v13, s[16:17]
	v_cndmask_b32_e64 v192, v192, v14, s[18:19]
	v_cndmask_b32_e64 v193, v193, v15, s[18:19]
	v_cndmask_b32_e64 v194, v194, v16, s[20:21]
	v_cndmask_b32_e64 v195, v195, v17, s[20:21]
	s_bitcmp0_b32 s22, 0
	s_cselect_b64 s[12:13], -1, 0
	ds_write_b128 v202, v[188:191] offset:16384
	ds_write_b128 v202, v[192:195] offset:16400
	s_waitcnt lgkmcnt(0)
	s_barrier
	ds_read_b128 v[10:13], v203 offset:16384
	ds_read_b128 v[14:17], v203 offset:16400
	s_waitcnt lgkmcnt(1)
	v_cmp_gt_u64_e64 s[14:15], v[188:189], v[10:11]
	v_cmp_gt_u64_e64 s[16:17], v[190:191], v[12:13]
	s_waitcnt lgkmcnt(0)
	v_cmp_gt_u64_e64 s[18:19], v[192:193], v[14:15]
	v_cmp_gt_u64_e64 s[20:21], v[194:195], v[16:17]
	s_xor_b64 s[14:15], s[14:15], s[12:13]
	s_xor_b64 s[16:17], s[16:17], s[12:13]
	s_xor_b64 s[18:19], s[18:19], s[12:13]
	s_xor_b64 s[20:21], s[20:21], s[12:13]
	v_cndmask_b32_e64 v188, v188, v10, s[14:15]
	v_cndmask_b32_e64 v189, v189, v11, s[14:15]
	v_cndmask_b32_e64 v190, v190, v12, s[16:17]
	v_cndmask_b32_e64 v191, v191, v13, s[16:17]
	v_cndmask_b32_e64 v192, v192, v14, s[18:19]
	v_cndmask_b32_e64 v193, v193, v15, s[18:19]
	v_cndmask_b32_e64 v194, v194, v16, s[20:21]
	v_cndmask_b32_e64 v195, v195, v17, s[20:21]
	s_not_b64 s[12:13], s[10:11]
	ds_bpermute_b32 v10, v201, v188
	ds_bpermute_b32 v11, v201, v189
	ds_bpermute_b32 v12, v201, v190
	ds_bpermute_b32 v13, v201, v191
	ds_bpermute_b32 v14, v201, v192
	ds_bpermute_b32 v15, v201, v193
	ds_bpermute_b32 v16, v201, v194
	ds_bpermute_b32 v17, v201, v195
	s_waitcnt lgkmcnt(6)
	v_cmp_gt_u64_e64 s[14:15], v[188:189], v[10:11]
	s_waitcnt lgkmcnt(4)
	v_cmp_gt_u64_e64 s[16:17], v[190:191], v[12:13]
	s_waitcnt lgkmcnt(2)
	v_cmp_gt_u64_e64 s[18:19], v[192:193], v[14:15]
	s_waitcnt lgkmcnt(0)
	v_cmp_gt_u64_e64 s[20:21], v[194:195], v[16:17]
	s_xor_b64 s[14:15], s[14:15], s[12:13]
	s_xor_b64 s[16:17], s[16:17], s[12:13]
	s_xor_b64 s[18:19], s[18:19], s[12:13]
	s_xor_b64 s[20:21], s[20:21], s[12:13]
	v_cndmask_b32_e64 v188, v188, v10, s[14:15]
	v_cndmask_b32_e64 v189, v189, v11, s[14:15]
	v_cndmask_b32_e64 v190, v190, v12, s[16:17]
	v_cndmask_b32_e64 v191, v191, v13, s[16:17]
	v_cndmask_b32_e64 v192, v192, v14, s[18:19]
	v_cndmask_b32_e64 v193, v193, v15, s[18:19]
	v_cndmask_b32_e64 v194, v194, v16, s[20:21]
	v_cndmask_b32_e64 v195, v195, v17, s[20:21]
	s_not_b64 s[12:13], s[8:9]
	ds_bpermute_b32 v10, v200, v188
	ds_bpermute_b32 v11, v200, v189
	ds_bpermute_b32 v12, v200, v190
	ds_bpermute_b32 v13, v200, v191
	ds_bpermute_b32 v14, v200, v192
	ds_bpermute_b32 v15, v200, v193
	ds_bpermute_b32 v16, v200, v194
	ds_bpermute_b32 v17, v200, v195
	s_waitcnt lgkmcnt(6)
	v_cmp_gt_u64_e64 s[14:15], v[188:189], v[10:11]
	s_waitcnt lgkmcnt(4)
	v_cmp_gt_u64_e64 s[16:17], v[190:191], v[12:13]
	s_waitcnt lgkmcnt(2)
	v_cmp_gt_u64_e64 s[18:19], v[192:193], v[14:15]
	s_waitcnt lgkmcnt(0)
	v_cmp_gt_u64_e64 s[20:21], v[194:195], v[16:17]
	s_xor_b64 s[14:15], s[14:15], s[12:13]
	s_xor_b64 s[16:17], s[16:17], s[12:13]
	s_xor_b64 s[18:19], s[18:19], s[12:13]
	s_xor_b64 s[20:21], s[20:21], s[12:13]
	v_cndmask_b32_e64 v188, v188, v10, s[14:15]
	v_cndmask_b32_e64 v189, v189, v11, s[14:15]
	v_cndmask_b32_e64 v190, v190, v12, s[16:17]
	v_cndmask_b32_e64 v191, v191, v13, s[16:17]
	v_cndmask_b32_e64 v192, v192, v14, s[18:19]
	v_cndmask_b32_e64 v193, v193, v15, s[18:19]
	v_cndmask_b32_e64 v194, v194, v16, s[20:21]
	v_cndmask_b32_e64 v195, v195, v17, s[20:21]
	s_not_b64 s[12:13], s[6:7]
	ds_bpermute_b32 v10, v199, v188
	ds_bpermute_b32 v11, v199, v189
	ds_bpermute_b32 v12, v199, v190
	ds_bpermute_b32 v13, v199, v191
	ds_bpermute_b32 v14, v199, v192
	ds_bpermute_b32 v15, v199, v193
	ds_bpermute_b32 v16, v199, v194
	ds_bpermute_b32 v17, v199, v195
	s_waitcnt lgkmcnt(6)
	v_cmp_gt_u64_e64 s[14:15], v[188:189], v[10:11]
	s_waitcnt lgkmcnt(4)
	v_cmp_gt_u64_e64 s[16:17], v[190:191], v[12:13]
	s_waitcnt lgkmcnt(2)
	v_cmp_gt_u64_e64 s[18:19], v[192:193], v[14:15]
	s_waitcnt lgkmcnt(0)
	v_cmp_gt_u64_e64 s[20:21], v[194:195], v[16:17]
	s_xor_b64 s[14:15], s[14:15], s[12:13]
	s_xor_b64 s[16:17], s[16:17], s[12:13]
	s_xor_b64 s[18:19], s[18:19], s[12:13]
	s_xor_b64 s[20:21], s[20:21], s[12:13]
	v_cndmask_b32_e64 v188, v188, v10, s[14:15]
	v_cndmask_b32_e64 v189, v189, v11, s[14:15]
	v_cndmask_b32_e64 v190, v190, v12, s[16:17]
	v_cndmask_b32_e64 v191, v191, v13, s[16:17]
	v_cndmask_b32_e64 v192, v192, v14, s[18:19]
	v_cndmask_b32_e64 v193, v193, v15, s[18:19]
	v_cndmask_b32_e64 v194, v194, v16, s[20:21]
	v_cndmask_b32_e64 v195, v195, v17, s[20:21]
	s_not_b64 s[12:13], s[4:5]
	ds_bpermute_b32 v10, v198, v188
	ds_bpermute_b32 v11, v198, v189
	ds_bpermute_b32 v12, v198, v190
	ds_bpermute_b32 v13, v198, v191
	ds_bpermute_b32 v14, v198, v192
	ds_bpermute_b32 v15, v198, v193
	ds_bpermute_b32 v16, v198, v194
	ds_bpermute_b32 v17, v198, v195
	s_waitcnt lgkmcnt(6)
	v_cmp_gt_u64_e64 s[14:15], v[188:189], v[10:11]
	s_waitcnt lgkmcnt(4)
	v_cmp_gt_u64_e64 s[16:17], v[190:191], v[12:13]
	s_waitcnt lgkmcnt(2)
	v_cmp_gt_u64_e64 s[18:19], v[192:193], v[14:15]
	s_waitcnt lgkmcnt(0)
	v_cmp_gt_u64_e64 s[20:21], v[194:195], v[16:17]
	s_xor_b64 s[14:15], s[14:15], s[12:13]
	s_xor_b64 s[16:17], s[16:17], s[12:13]
	s_xor_b64 s[18:19], s[18:19], s[12:13]
	s_xor_b64 s[20:21], s[20:21], s[12:13]
	v_cndmask_b32_e64 v188, v188, v10, s[14:15]
	v_cndmask_b32_e64 v189, v189, v11, s[14:15]
	v_cndmask_b32_e64 v190, v190, v12, s[16:17]
	v_cndmask_b32_e64 v191, v191, v13, s[16:17]
	v_cndmask_b32_e64 v192, v192, v14, s[18:19]
	v_cndmask_b32_e64 v193, v193, v15, s[18:19]
	v_cndmask_b32_e64 v194, v194, v16, s[20:21]
	v_cndmask_b32_e64 v195, v195, v17, s[20:21]
	s_not_b64 s[12:13], s[2:3]
	ds_bpermute_b32 v10, v197, v188
	ds_bpermute_b32 v11, v197, v189
	ds_bpermute_b32 v12, v197, v190
	ds_bpermute_b32 v13, v197, v191
	ds_bpermute_b32 v14, v197, v192
	ds_bpermute_b32 v15, v197, v193
	ds_bpermute_b32 v16, v197, v194
	ds_bpermute_b32 v17, v197, v195
	s_waitcnt lgkmcnt(6)
	v_cmp_gt_u64_e64 s[14:15], v[188:189], v[10:11]
	s_waitcnt lgkmcnt(4)
	v_cmp_gt_u64_e64 s[16:17], v[190:191], v[12:13]
	s_waitcnt lgkmcnt(2)
	v_cmp_gt_u64_e64 s[18:19], v[192:193], v[14:15]
	s_waitcnt lgkmcnt(0)
	v_cmp_gt_u64_e64 s[20:21], v[194:195], v[16:17]
	s_xor_b64 s[14:15], s[14:15], s[12:13]
	s_xor_b64 s[16:17], s[16:17], s[12:13]
	s_xor_b64 s[18:19], s[18:19], s[12:13]
	s_xor_b64 s[20:21], s[20:21], s[12:13]
	v_cndmask_b32_e64 v188, v188, v10, s[14:15]
	v_cndmask_b32_e64 v189, v189, v11, s[14:15]
	v_cndmask_b32_e64 v190, v190, v12, s[16:17]
	v_cndmask_b32_e64 v191, v191, v13, s[16:17]
	v_cndmask_b32_e64 v192, v192, v14, s[18:19]
	v_cndmask_b32_e64 v193, v193, v15, s[18:19]
	v_cndmask_b32_e64 v194, v194, v16, s[20:21]
	v_cndmask_b32_e64 v195, v195, v17, s[20:21]
	s_not_b64 s[12:13], s[0:1]
	ds_bpermute_b32 v10, v196, v188
	ds_bpermute_b32 v11, v196, v189
	ds_bpermute_b32 v12, v196, v190
	ds_bpermute_b32 v13, v196, v191
	ds_bpermute_b32 v14, v196, v192
	ds_bpermute_b32 v15, v196, v193
	ds_bpermute_b32 v16, v196, v194
	ds_bpermute_b32 v17, v196, v195
	s_waitcnt lgkmcnt(6)
	v_cmp_gt_u64_e64 s[14:15], v[188:189], v[10:11]
	s_waitcnt lgkmcnt(4)
	v_cmp_gt_u64_e64 s[16:17], v[190:191], v[12:13]
	s_waitcnt lgkmcnt(2)
	v_cmp_gt_u64_e64 s[18:19], v[192:193], v[14:15]
	s_waitcnt lgkmcnt(0)
	v_cmp_gt_u64_e64 s[20:21], v[194:195], v[16:17]
	s_xor_b64 s[14:15], s[14:15], s[12:13]
	s_xor_b64 s[16:17], s[16:17], s[12:13]
	s_xor_b64 s[18:19], s[18:19], s[12:13]
	s_xor_b64 s[20:21], s[20:21], s[12:13]
	v_cndmask_b32_e64 v188, v188, v10, s[14:15]
	v_cndmask_b32_e64 v189, v189, v11, s[14:15]
	v_cndmask_b32_e64 v190, v190, v12, s[16:17]
	v_cndmask_b32_e64 v191, v191, v13, s[16:17]
	v_cndmask_b32_e64 v192, v192, v14, s[18:19]
	v_cndmask_b32_e64 v193, v193, v15, s[18:19]
	v_cndmask_b32_e64 v194, v194, v16, s[20:21]
	v_cndmask_b32_e64 v195, v195, v17, s[20:21]
	s_mov_b64 s[12:13], -1
	v_cmp_gt_u64_e64 s[14:15], v[188:189], v[192:193]
	v_cmp_gt_u64_e64 s[16:17], v[190:191], v[194:195]
	s_xor_b64 s[14:15], s[14:15], s[12:13]
	s_xor_b64 s[16:17], s[16:17], s[12:13]
	v_cndmask_b32_e64 v2, v188, v192, s[14:15]
	v_cndmask_b32_e64 v3, v189, v193, s[14:15]
	v_cndmask_b32_e64 v6, v192, v188, s[14:15]
	v_cndmask_b32_e64 v7, v193, v189, s[14:15]
	v_cndmask_b32_e64 v4, v190, v194, s[16:17]
	v_cndmask_b32_e64 v5, v191, v195, s[16:17]
	v_cndmask_b32_e64 v8, v194, v190, s[16:17]
	v_cndmask_b32_e64 v9, v195, v191, s[16:17]
	s_mov_b64 s[12:13], -1
	v_cmp_gt_u64_e64 s[14:15], v[2:3], v[4:5]
	v_cmp_gt_u64_e64 s[16:17], v[6:7], v[8:9]
	s_xor_b64 s[14:15], s[14:15], s[12:13]
	s_xor_b64 s[16:17], s[16:17], s[12:13]
	v_cndmask_b32_e64 v188, v2, v4, s[14:15]
	v_cndmask_b32_e64 v189, v3, v5, s[14:15]
	v_cndmask_b32_e64 v190, v4, v2, s[14:15]
	v_cndmask_b32_e64 v191, v5, v3, s[14:15]
	v_cndmask_b32_e64 v192, v6, v8, s[16:17]
	v_cndmask_b32_e64 v193, v7, v9, s[16:17]
	v_cndmask_b32_e64 v194, v8, v6, s[16:17]
	v_cndmask_b32_e64 v195, v9, v7, s[16:17]
	s_lshr_b32 s31, s26, 2
	v_cmp_gt_u32_e64 s[14:15], s31, v18
	v_cmp_gt_u32_e64 s[16:17], s27, v18
	v_lshlrev_b32_e32 v206, 2, v18
	v_not_b32_e32 v10, v188
	v_not_b32_e32 v11, v190
	v_not_b32_e32 v12, v192
	v_not_b32_e32 v13, v194
	v_lshl_add_u32 v210, v10, 6, s33
	v_lshl_add_u32 v211, v11, 6, s33
	v_lshl_add_u32 v212, v12, 6, s33
	v_lshl_add_u32 v213, v13, 6, s33
	v_mov_b32_e32 v214, v206
	v_add_u32_e32 v215, 1, v206
	v_add_u32_e32 v216, 2, v206
	v_add_u32_e32 v217, 3, v206
	v_cndmask_b32_e64 v214, -1, v214, s[16:17]
	v_cndmask_b32_e64 v215, -1, v215, s[16:17]
	v_cndmask_b32_e64 v216, -1, v216, s[16:17]
	v_cndmask_b32_e64 v217, -1, v217, s[16:17]
	v_add_u32_e32 v10, s28, v10
	v_add_u32_e32 v11, s28, v11
	v_add_u32_e32 v12, s28, v12
	v_add_u32_e32 v13, s28, v13
	s_mul_i32 s31, s30, 0x1200
	s_add_i32 s31, s31, s29
	s_lshl_b32 s31, s31, 2
	v_lshl_add_u32 v207, v18, 4, s31
	s_add_u32 s98, s34, 0x700000
	s_addc_u32 s99, s35, 0
	s_and_saveexec_b64 s[20:21], s[14:15]
	s_nop 0
	global_store_dword v210, v214, s[98:99]
	global_store_dword v211, v215, s[98:99]
	global_store_dword v212, v216, s[98:99]
	global_store_dword v213, v217, s[98:99]
	s_add_u32 s98, s34, 0xa00000
	s_addc_u32 s99, s35, 0
	s_and_b64 exec, exec, s[16:17]
	s_nop 0
	global_store_dwordx4 v207, v[10:13], s[98:99]
	s_nop 1
	s_mov_b64 exec, -1
	s_add_i32 s24, s24, s47
	s_branch .Ltks_item
.Ltks_done:
.LBB0_1364:
	s_waitcnt vmcnt(0)
	v_readlane_b32 s0, v255, 13
	v_readlane_b32 s1, v255, 14
	s_and_b64 vcc, exec, s[0:1]
	s_barrier
	s_cbranch_vccnz .LBB0_1410
	v_mbcnt_lo_u32_b32 v0, -1, 0
	v_mbcnt_hi_u32_b32 v0, -1, v0
	s_nop 0
	v_cmp_eq_u32_e32 vcc, 0, v0
	s_and_saveexec_b64 s[38:39], vcc
	s_cbranch_execz .LBB0_1409
	v_readlane_b32 s68, v255, 8
	v_readlane_b32 s1, v255, 19
	v_readlane_b32 s0, v255, 10
	v_readlane_b32 s69, v255, 9
	v_mov_b32_e32 v0, s1
	s_waitcnt vmcnt(0) expcnt(0) lgkmcnt(0)
	ds_read_b32 v2, v0
	v_readlane_b32 s1, v255, 20
	s_waitcnt lgkmcnt(0)
	v_cmp_ne_u32_e32 vcc, 0, v2
	v_mov_b32_e32 v0, s1
	ds_read_b32 v0, v0
	s_cbranch_vccnz .LBB0_1380
	v_readlane_b32 s4, v255, 0
	v_readlane_b32 s5, v255, 1
	s_load_dwordx2 s[2:3], s[4:5], 0x4
	s_add_u32 s4, s68, 0x1000
	s_addc_u32 s5, s69, 0
	s_add_u32 s6, s68, 0x1100
	s_addc_u32 s7, s69, 0
	s_add_u32 s8, s68, 0x1200
	s_addc_u32 s9, s69, 0
	s_waitcnt lgkmcnt(0)
	s_mul_i32 s1, s2, s47
	s_add_u32 s10, s68, 0x1300
	s_mul_i32 s1, s1, s3
	s_addc_u32 s11, s69, 0
	s_mov_b32 s2, 1
	s_mov_b64 s[12:13], 0
	s_branch .LBB0_1370
